# GEMM tile boundary: first K-tile waits of each later tile counted as vmcnt(8 + epilogue ops) so the previous tile's epilogue stores drain behind the first two MFMA blocks
# speedup vs baseline: 1.0021x; 1.0021x over previous
.LBB0_342:
	v_and_b32_e32 v7, 15, v6
	v_readlane_b32 s0, v251, 46
	v_lshrrev_b32_e32 v16, 1, v6
	v_and_b32_e32 v16, 24, v16
	v_or_b32_e32 v153, s0, v7
	v_lshlrev_b32_e32 v17, 6, v153
	v_lshlrev_b32_e32 v18, 1, v16
	s_movk_i32 s0, 0x3c0
	v_lshlrev_b32_e32 v19, 2, v153
	v_and_or_b32 v17, v17, s0, v18
	v_and_b32_e32 v19, 32, v19
	v_readlane_b32 s0, v251, 47
	v_lshlrev_b32_e32 v6, 2, v6
	v_mov_b32_e32 v143, v97
	v_bitop3_b32 v17, v17, s0, v19 bitop3:0xde
	v_lshl_or_b32 v7, v7, 6, v18
	v_and_b32_e32 v6, 32, v6
	v_readlane_b32 s0, v251, 49
	v_lshl_add_u64 v[8:9], s[44:45], 0, v[142:143]
	v_mov_b32_e32 v139, v97
	v_bitop3_b32 v158, v7, s0, v6 bitop3:0xde
	s_add_u32 s0, s58, 0x25400000
	v_lshl_add_u64 v[10:11], s[44:45], 0, v[138:139]
	v_mov_b32_e32 v145, v97
	s_addc_u32 s1, s59, 0
	v_lshl_add_u64 v[6:7], v[8:9], 0, s[64:65]
	s_add_i32 m0, s35, 0x18000
	v_lshl_add_u64 v[12:13], s[42:43], 0, v[144:145]
	v_mov_b32_e32 v141, v97
	v_mov_b32_e32 v243, 0
	s_waitcnt vmcnt(2)
	s_barrier
	global_load_lds_dwordx4 v[6:7], off
	v_lshl_add_u64 v[6:7], v[10:11], 0, s[64:65]
	s_add_i32 m0, s35, 0x1a000
	s_add_i32 s79, s35, 0x8000
	s_add_i32 s81, s35, 0xa000
	v_lshl_add_u64 v[14:15], s[42:43], 0, v[140:141]
	global_load_lds_dwordx4 v[6:7], off
	v_lshl_add_u64 v[6:7], v[12:13], 0, s[64:65]
	s_mov_b32 m0, s79
	s_add_u32 s2, s44, 0x80080
	global_load_lds_dwordx4 v[6:7], off
	v_lshl_add_u64 v[6:7], v[14:15], 0, s[64:65]
	s_mov_b32 m0, s81
	s_addc_u32 s3, s45, 0
	global_load_lds_dwordx4 v[6:7], off
	v_lshl_add_u64 v[6:7], s[2:3], 0, v[142:143]
	s_add_i32 m0, s35, 0x1c000
	v_readlane_b32 s4, v250, 11
	global_load_lds_dwordx4 v[6:7], off
	v_lshl_add_u64 v[6:7], s[2:3], 0, v[138:139]
	s_add_i32 m0, s35, 0x1e000
	v_readlane_b32 s2, v251, 48
	global_load_lds_dwordx4 v[6:7], off
	v_lshlrev_b32_e32 v7, 15, v3
	v_and_b32_e32 v7, 0xffff0000, v7
	v_lshl_add_u32 v4, v4, 12, v7
	v_and_b32_e32 v3, 1, v3
	v_lshl_or_b32 v3, v3, 6, v4
	v_lshl_add_u32 v146, v5, 1, v3
	v_lshlrev_b32_e32 v3, 15, v0
	v_and_b32_e32 v3, 0xffff0000, v3
	s_waitcnt vmcnt(6)
	v_lshl_add_u32 v1, v1, 12, v3
	v_and_b32_e32 v0, 1, v0
	v_or_b32_e32 v6, s2, v16
	v_lshl_or_b32 v0, v0, 6, v1
	v_mov_b32_e32 v147, v97
	v_lshl_add_u32 v148, v2, 1, v0
	v_mov_b32_e32 v149, v97
	s_mov_b32 s2, 0
	v_add_u32_e32 v159, 0, v17
	v_lshlrev_b32_e32 v96, 1, v6
	v_readlane_b32 s12, v252, 54
	s_mov_b32 s3, s4
	s_movk_i32 s13, 0x1800
	s_barrier
	v_readlane_b32 s5, v250, 12
	s_branch .LBB0_345

.LBB0_352:
	s_add_u32 s44, s42, 0xfff80080
	s_addc_u32 s45, s43, -1
	s_add_i32 s55, 0, 0x10000
	s_cmp_eq_u32 s54, 28
	s_cselect_b32 s53, s17, s45
	s_cselect_b32 s52, s18, s44
	v_add_u32_e32 v150, s55, v158
	s_cselect_b32 s45, s5, s33
	s_cselect_b32 s44, s20, s28
	s_add_i32 s61, 0, 0x14000
	ds_read_b128 v[130:133], v150
	ds_read_b128 v[160:163], v150 offset:1024
	ds_read_b128 v[164:167], v150 offset:2048
	ds_read_b128 v[168:171], v150 offset:3072
	v_add_u32_e32 v150, s61, v158
	ds_read_b128 v[172:175], v150
	ds_read_b128 v[176:179], v150 offset:1024
	ds_read_b128 v[180:183], v150 offset:2048
	ds_read_b128 v[184:187], v150 offset:3072
	v_lshl_add_u64 v[150:151], s[42:43], 0, v[146:147]
	s_add_i32 m0, s35, 0xc000
	ds_read_b128 v[188:191], v159
	ds_read_b128 v[192:195], v159 offset:1024
	ds_read_b128 v[196:199], v159 offset:2048
	ds_read_b128 v[210:213], v159 offset:3072
	ds_read_b128 v[214:217], v159 offset:4096
	ds_read_b128 v[218:221], v159 offset:5120
	ds_read_b128 v[222:225], v159 offset:6144
	ds_read_b128 v[226:229], v159 offset:7168
	global_load_lds_dwordx4 v[150:151], off
	v_lshl_add_u64 v[150:151], s[42:43], 0, v[148:149]
	s_add_i32 m0, s35, 0xe000
	s_nop 0
	global_load_lds_dwordx4 v[150:151], off
	v_cmp_ne_u32_e32 vcc, 0, v243
	s_cbranch_vccnz .Lrx_G_IN_0
	s_waitcnt vmcnt(8)
.Lrx_G_IN_0:
	s_waitcnt vmcnt(16)
	s_waitcnt lgkmcnt(0)
	s_setprio 1
	s_barrier
	v_mfma_f32_16x16x32_bf16 v[126:129], v[130:133], v[188:191], v[126:129]
	v_mfma_f32_16x16x32_bf16 v[122:125], v[164:167], v[188:191], v[122:125]
	v_mfma_f32_16x16x32_bf16 v[110:113], v[130:133], v[196:199], v[110:113]
	v_mfma_f32_16x16x32_bf16 v[106:109], v[164:167], v[196:199], v[106:109]
	v_mfma_f32_16x16x32_bf16 v[92:95], v[130:133], v[214:217], v[92:95]
	v_mfma_f32_16x16x32_bf16 v[88:91], v[164:167], v[214:217], v[88:91]
	v_mfma_f32_16x16x32_bf16 v[76:79], v[130:133], v[222:225], v[76:79]
	v_mfma_f32_16x16x32_bf16 v[72:75], v[164:167], v[222:225], v[72:75]
	v_mfma_f32_16x16x32_bf16 v[126:129], v[160:163], v[192:195], v[126:129]
	v_mfma_f32_16x16x32_bf16 v[122:125], v[168:171], v[192:195], v[122:125]
	v_mfma_f32_16x16x32_bf16 v[110:113], v[160:163], v[210:213], v[110:113]
	v_mfma_f32_16x16x32_bf16 v[106:109], v[168:171], v[210:213], v[106:109]
	v_mfma_f32_16x16x32_bf16 v[92:95], v[160:163], v[218:221], v[92:95]
	v_mfma_f32_16x16x32_bf16 v[88:91], v[168:171], v[218:221], v[88:91]
	v_mfma_f32_16x16x32_bf16 v[76:79], v[160:163], v[226:229], v[76:79]
	v_mfma_f32_16x16x32_bf16 v[72:75], v[168:171], v[226:229], v[72:75]
	v_mfma_f32_16x16x32_bf16 v[118:121], v[172:175], v[188:191], v[118:121]
	v_mfma_f32_16x16x32_bf16 v[114:117], v[180:183], v[188:191], v[114:117]
	v_mfma_f32_16x16x32_bf16 v[102:105], v[172:175], v[196:199], v[102:105]
	v_mfma_f32_16x16x32_bf16 v[98:101], v[180:183], v[196:199], v[98:101]
	v_mfma_f32_16x16x32_bf16 v[84:87], v[172:175], v[214:217], v[84:87]
	v_mfma_f32_16x16x32_bf16 v[80:83], v[180:183], v[214:217], v[80:83]
	v_mfma_f32_16x16x32_bf16 v[68:71], v[172:175], v[222:225], v[68:71]
	v_mfma_f32_16x16x32_bf16 v[64:67], v[180:183], v[222:225], v[64:67]
	v_mfma_f32_16x16x32_bf16 v[118:121], v[176:179], v[192:195], v[118:121]
	v_mfma_f32_16x16x32_bf16 v[114:117], v[184:187], v[192:195], v[114:117]
	v_mfma_f32_16x16x32_bf16 v[102:105], v[176:179], v[210:213], v[102:105]
	v_mfma_f32_16x16x32_bf16 v[98:101], v[184:187], v[210:213], v[98:101]
	v_mfma_f32_16x16x32_bf16 v[84:87], v[176:179], v[218:221], v[84:87]
	v_mfma_f32_16x16x32_bf16 v[80:83], v[184:187], v[218:221], v[80:83]
	v_mfma_f32_16x16x32_bf16 v[68:71], v[176:179], v[226:229], v[68:71]
	v_mfma_f32_16x16x32_bf16 v[64:67], v[184:187], v[226:229], v[64:67]
	s_barrier
	s_setprio 0
	s_add_i32 s55, s55, s75
	v_lshl_add_u64 v[150:151], s[44:45], 0, v[142:143]
	s_mov_b32 m0, s55
	ds_read_b128 v[188:191], v159 offset:16384
	ds_read_b128 v[192:195], v159 offset:17408
	ds_read_b128 v[196:199], v159 offset:18432
	ds_read_b128 v[210:213], v159 offset:19456
	ds_read_b128 v[214:217], v159 offset:20480
	ds_read_b128 v[218:221], v159 offset:21504
	ds_read_b128 v[222:225], v159 offset:22528
	ds_read_b128 v[226:229], v159 offset:23552
	global_load_lds_dwordx4 v[150:151], off
	s_add_i32 m0, s55, 0x2000
	s_add_u32 s56, s44, 0x80000
	v_lshl_add_u64 v[154:155], s[44:45], 0, v[138:139]
	s_addc_u32 s57, s45, 0
	s_add_i32 s55, s61, s75
	global_load_lds_dwordx4 v[154:155], off
	v_lshl_add_u64 v[156:157], s[56:57], 0, v[142:143]
	s_mov_b32 m0, s55
	v_lshl_add_u64 v[202:203], s[52:53], 0, v[140:141]
	global_load_lds_dwordx4 v[156:157], off
	v_lshl_add_u64 v[156:157], s[56:57], 0, v[138:139]
	s_add_i32 m0, s55, 0x2000
	s_nop 0
	global_load_lds_dwordx4 v[156:157], off
	v_lshl_add_u64 v[156:157], s[52:53], 0, v[144:145]
	s_mov_b32 m0, s35
	s_nop 0
	global_load_lds_dwordx4 v[156:157], off
	s_mov_b32 m0, s68
	s_nop 0
	global_load_lds_dwordx4 v[202:203], off
	v_cmp_ne_u32_e32 vcc, 0, v243
	s_cbranch_vccnz .Lrx_G_IN_1
	s_waitcnt vmcnt(8)
.Lrx_G_IN_1:
	s_waitcnt vmcnt(16)
	v_mov_b32_e32 v243, 0
	s_waitcnt lgkmcnt(0)
	s_setprio 1
	s_barrier
	v_mfma_f32_16x16x32_bf16 v[60:63], v[130:133], v[188:191], v[60:63]
	v_mfma_f32_16x16x32_bf16 v[56:59], v[164:167], v[188:191], v[56:59]
	v_mfma_f32_16x16x32_bf16 v[44:47], v[130:133], v[196:199], v[44:47]
	v_mfma_f32_16x16x32_bf16 v[40:43], v[164:167], v[196:199], v[40:43]
	v_mfma_f32_16x16x32_bf16 v[28:31], v[130:133], v[214:217], v[28:31]
	v_mfma_f32_16x16x32_bf16 v[24:27], v[164:167], v[214:217], v[24:27]
	v_mfma_f32_16x16x32_bf16 v[12:15], v[130:133], v[222:225], v[12:15]
	v_mfma_f32_16x16x32_bf16 v[8:11], v[164:167], v[222:225], v[8:11]
	v_mfma_f32_16x16x32_bf16 v[60:63], v[160:163], v[192:195], v[60:63]
	v_mfma_f32_16x16x32_bf16 v[56:59], v[168:171], v[192:195], v[56:59]
	v_mfma_f32_16x16x32_bf16 v[44:47], v[160:163], v[210:213], v[44:47]
	v_mfma_f32_16x16x32_bf16 v[40:43], v[168:171], v[210:213], v[40:43]
	v_mfma_f32_16x16x32_bf16 v[28:31], v[160:163], v[218:221], v[28:31]
	v_mfma_f32_16x16x32_bf16 v[24:27], v[168:171], v[218:221], v[24:27]
	v_mfma_f32_16x16x32_bf16 v[12:15], v[160:163], v[226:229], v[12:15]
	v_mfma_f32_16x16x32_bf16 v[8:11], v[168:171], v[226:229], v[8:11]
	v_mfma_f32_16x16x32_bf16 v[52:55], v[172:175], v[188:191], v[52:55]
	v_mfma_f32_16x16x32_bf16 v[48:51], v[180:183], v[188:191], v[48:51]
	v_mfma_f32_16x16x32_bf16 v[36:39], v[172:175], v[196:199], v[36:39]
	v_mfma_f32_16x16x32_bf16 v[32:35], v[180:183], v[196:199], v[32:35]
	v_mfma_f32_16x16x32_bf16 v[20:23], v[172:175], v[214:217], v[20:23]
	v_mfma_f32_16x16x32_bf16 v[16:19], v[180:183], v[214:217], v[16:19]
	v_mfma_f32_16x16x32_bf16 v[4:7], v[172:175], v[222:225], v[4:7]
	v_mfma_f32_16x16x32_bf16 v[0:3], v[180:183], v[222:225], v[0:3]
	v_mfma_f32_16x16x32_bf16 v[52:55], v[176:179], v[192:195], v[52:55]
	v_mfma_f32_16x16x32_bf16 v[48:51], v[184:187], v[192:195], v[48:51]
	v_mfma_f32_16x16x32_bf16 v[36:39], v[176:179], v[210:213], v[36:39]
	v_mfma_f32_16x16x32_bf16 v[32:35], v[184:187], v[210:213], v[32:35]
	v_mfma_f32_16x16x32_bf16 v[20:23], v[176:179], v[218:221], v[20:23]
	v_mfma_f32_16x16x32_bf16 v[16:19], v[184:187], v[218:221], v[16:19]
	v_mfma_f32_16x16x32_bf16 v[4:7], v[176:179], v[226:229], v[4:7]
	v_mfma_f32_16x16x32_bf16 v[0:3], v[184:187], v[226:229], v[0:3]
	s_barrier
	s_setprio 0
	s_add_i32 s55, 0, 0x18000
	s_add_i32 s56, 0, 0x1c000
	v_add_u32_e32 v168, s55, v158
	v_add_u32_e32 v184, s56, v158
	ds_read_b128 v[130:133], v168
	ds_read_b128 v[160:163], v168 offset:1024
	ds_read_b128 v[164:167], v168 offset:2048
	ds_read_b128 v[168:171], v168 offset:3072
	ds_read_b128 v[172:175], v184
	ds_read_b128 v[176:179], v184 offset:1024
	ds_read_b128 v[180:183], v184 offset:2048
	ds_read_b128 v[184:187], v184 offset:3072
	s_add_u32 s52, s52, 0x80000
	s_addc_u32 s53, s53, 0
	s_mov_b32 m0, s69
	v_lshl_add_u64 v[204:205], s[52:53], 0, v[144:145]
	ds_read_b128 v[188:191], v159 offset:32768
	ds_read_b128 v[192:195], v159 offset:33792
	ds_read_b128 v[196:199], v159 offset:34816
	ds_read_b128 v[210:213], v159 offset:35840
	ds_read_b128 v[214:217], v159 offset:36864
	ds_read_b128 v[218:221], v159 offset:37888
	ds_read_b128 v[222:225], v159 offset:38912
	ds_read_b128 v[226:229], v159 offset:39936
	global_load_lds_dwordx4 v[204:205], off
	v_lshl_add_u64 v[204:205], s[52:53], 0, v[140:141]
	s_mov_b32 m0, s77
	s_nop 0
	global_load_lds_dwordx4 v[204:205], off
	s_waitcnt vmcnt(8)
	s_waitcnt lgkmcnt(0)
	s_setprio 1
	s_barrier
	v_mfma_f32_16x16x32_bf16 v[126:129], v[130:133], v[188:191], v[126:129]
	v_mfma_f32_16x16x32_bf16 v[122:125], v[164:167], v[188:191], v[122:125]
	v_mfma_f32_16x16x32_bf16 v[110:113], v[130:133], v[196:199], v[110:113]
	v_mfma_f32_16x16x32_bf16 v[106:109], v[164:167], v[196:199], v[106:109]
	v_mfma_f32_16x16x32_bf16 v[92:95], v[130:133], v[214:217], v[92:95]
	v_mfma_f32_16x16x32_bf16 v[88:91], v[164:167], v[214:217], v[88:91]
	v_mfma_f32_16x16x32_bf16 v[76:79], v[130:133], v[222:225], v[76:79]
	v_mfma_f32_16x16x32_bf16 v[72:75], v[164:167], v[222:225], v[72:75]
	v_mfma_f32_16x16x32_bf16 v[126:129], v[160:163], v[192:195], v[126:129]
	v_mfma_f32_16x16x32_bf16 v[122:125], v[168:171], v[192:195], v[122:125]
	v_mfma_f32_16x16x32_bf16 v[110:113], v[160:163], v[210:213], v[110:113]
	v_mfma_f32_16x16x32_bf16 v[106:109], v[168:171], v[210:213], v[106:109]
	v_mfma_f32_16x16x32_bf16 v[92:95], v[160:163], v[218:221], v[92:95]
	v_mfma_f32_16x16x32_bf16 v[88:91], v[168:171], v[218:221], v[88:91]
	v_mfma_f32_16x16x32_bf16 v[76:79], v[160:163], v[226:229], v[76:79]
	v_mfma_f32_16x16x32_bf16 v[72:75], v[168:171], v[226:229], v[72:75]
	v_mfma_f32_16x16x32_bf16 v[118:121], v[172:175], v[188:191], v[118:121]
	v_mfma_f32_16x16x32_bf16 v[114:117], v[180:183], v[188:191], v[114:117]
	v_mfma_f32_16x16x32_bf16 v[102:105], v[172:175], v[196:199], v[102:105]
	v_mfma_f32_16x16x32_bf16 v[98:101], v[180:183], v[196:199], v[98:101]
	v_mfma_f32_16x16x32_bf16 v[84:87], v[172:175], v[214:217], v[84:87]
	v_mfma_f32_16x16x32_bf16 v[80:83], v[180:183], v[214:217], v[80:83]
	v_mfma_f32_16x16x32_bf16 v[68:71], v[172:175], v[222:225], v[68:71]
	v_mfma_f32_16x16x32_bf16 v[64:67], v[180:183], v[222:225], v[64:67]
	v_mfma_f32_16x16x32_bf16 v[118:121], v[176:179], v[192:195], v[118:121]
	v_mfma_f32_16x16x32_bf16 v[114:117], v[184:187], v[192:195], v[114:117]
	v_mfma_f32_16x16x32_bf16 v[102:105], v[176:179], v[210:213], v[102:105]
	v_mfma_f32_16x16x32_bf16 v[98:101], v[184:187], v[210:213], v[98:101]
	v_mfma_f32_16x16x32_bf16 v[84:87], v[176:179], v[218:221], v[84:87]
	v_mfma_f32_16x16x32_bf16 v[80:83], v[184:187], v[218:221], v[80:83]
	v_mfma_f32_16x16x32_bf16 v[68:71], v[176:179], v[226:229], v[68:71]
	v_mfma_f32_16x16x32_bf16 v[64:67], v[184:187], v[226:229], v[64:67]
	s_barrier
	s_setprio 0
	s_add_i32 s52, s55, s75
	v_lshl_add_u64 v[150:151], v[150:151], 0, s[64:65]
	s_mov_b32 m0, s52
	ds_read_b128 v[188:191], v159 offset:49152
	ds_read_b128 v[192:195], v159 offset:50176
	ds_read_b128 v[196:199], v159 offset:51200
	ds_read_b128 v[210:213], v159 offset:52224
	ds_read_b128 v[214:217], v159 offset:53248
	ds_read_b128 v[218:221], v159 offset:54272
	ds_read_b128 v[222:225], v159 offset:55296
	ds_read_b128 v[226:229], v159 offset:56320
	global_load_lds_dwordx4 v[150:151], off
	s_add_i32 m0, s52, 0x2000
	s_add_u32 s44, s44, 0x80080
	v_lshl_add_u64 v[150:151], v[154:155], 0, s[64:65]
	s_addc_u32 s45, s45, 0
	s_add_i32 s52, s56, s75
	global_load_lds_dwordx4 v[150:151], off
	v_lshl_add_u64 v[150:151], s[44:45], 0, v[142:143]
	s_mov_b32 m0, s52
	s_nop 0
	global_load_lds_dwordx4 v[150:151], off
	v_lshl_add_u64 v[150:151], s[44:45], 0, v[138:139]
	s_add_i32 m0, s52, 0x2000
	s_nop 0
	global_load_lds_dwordx4 v[150:151], off
	v_lshl_add_u64 v[150:151], v[156:157], 0, s[64:65]
	s_mov_b32 m0, s79
	s_nop 0
	global_load_lds_dwordx4 v[150:151], off
	v_lshl_add_u64 v[150:151], v[202:203], 0, s[64:65]
	s_mov_b32 m0, s81
	s_nop 0
	global_load_lds_dwordx4 v[150:151], off
	s_waitcnt vmcnt(8)
	s_waitcnt lgkmcnt(0)
	s_setprio 1
	s_barrier
	v_mfma_f32_16x16x32_bf16 v[60:63], v[130:133], v[188:191], v[60:63]
	v_mfma_f32_16x16x32_bf16 v[56:59], v[164:167], v[188:191], v[56:59]
	v_mfma_f32_16x16x32_bf16 v[44:47], v[130:133], v[196:199], v[44:47]
	v_mfma_f32_16x16x32_bf16 v[40:43], v[164:167], v[196:199], v[40:43]
	v_mfma_f32_16x16x32_bf16 v[28:31], v[130:133], v[214:217], v[28:31]
	v_mfma_f32_16x16x32_bf16 v[24:27], v[164:167], v[214:217], v[24:27]
	v_mfma_f32_16x16x32_bf16 v[12:15], v[130:133], v[222:225], v[12:15]
	v_mfma_f32_16x16x32_bf16 v[8:11], v[164:167], v[222:225], v[8:11]
	v_mfma_f32_16x16x32_bf16 v[60:63], v[160:163], v[192:195], v[60:63]
	v_mfma_f32_16x16x32_bf16 v[56:59], v[168:171], v[192:195], v[56:59]
	v_mfma_f32_16x16x32_bf16 v[44:47], v[160:163], v[210:213], v[44:47]
	v_mfma_f32_16x16x32_bf16 v[40:43], v[168:171], v[210:213], v[40:43]
	v_mfma_f32_16x16x32_bf16 v[28:31], v[160:163], v[218:221], v[28:31]
	v_mfma_f32_16x16x32_bf16 v[24:27], v[168:171], v[218:221], v[24:27]
	v_mfma_f32_16x16x32_bf16 v[12:15], v[160:163], v[226:229], v[12:15]
	v_mfma_f32_16x16x32_bf16 v[8:11], v[168:171], v[226:229], v[8:11]
	v_mfma_f32_16x16x32_bf16 v[52:55], v[172:175], v[188:191], v[52:55]
	v_mfma_f32_16x16x32_bf16 v[48:51], v[180:183], v[188:191], v[48:51]
	v_mfma_f32_16x16x32_bf16 v[36:39], v[172:175], v[196:199], v[36:39]
	v_mfma_f32_16x16x32_bf16 v[32:35], v[180:183], v[196:199], v[32:35]
	v_mfma_f32_16x16x32_bf16 v[20:23], v[172:175], v[214:217], v[20:23]
	v_mfma_f32_16x16x32_bf16 v[16:19], v[180:183], v[214:217], v[16:19]
	v_mfma_f32_16x16x32_bf16 v[4:7], v[172:175], v[222:225], v[4:7]
	v_mfma_f32_16x16x32_bf16 v[0:3], v[180:183], v[222:225], v[0:3]
	v_mfma_f32_16x16x32_bf16 v[52:55], v[176:179], v[192:195], v[52:55]
	v_mfma_f32_16x16x32_bf16 v[48:51], v[184:187], v[192:195], v[48:51]
	v_mfma_f32_16x16x32_bf16 v[36:39], v[176:179], v[210:213], v[36:39]
	v_mfma_f32_16x16x32_bf16 v[32:35], v[184:187], v[210:213], v[32:35]
	v_mfma_f32_16x16x32_bf16 v[20:23], v[176:179], v[218:221], v[20:23]
	v_mfma_f32_16x16x32_bf16 v[16:19], v[184:187], v[218:221], v[16:19]
	v_mfma_f32_16x16x32_bf16 v[4:7], v[176:179], v[226:229], v[4:7]
	v_mfma_f32_16x16x32_bf16 v[0:3], v[184:187], v[226:229], v[0:3]
	s_barrier
	s_setprio 0
	s_add_i32 s54, s54, 2
	s_add_u32 s42, s42, 0x100
	s_addc_u32 s43, s43, 0
	s_add_u32 s28, s28, 0x100
	s_addc_u32 s33, s33, 0
	s_cmp_gt_u32 s54, 29
	s_cbranch_scc0 .LBB0_352
	v_mov_b32_e32 v243, 1
	v_readlane_b32 s6, v251, 54
	v_readlane_b32 s7, v251, 55
	s_and_b64 vcc, exec, s[6:7]
	s_cbranch_vccz .LBB0_355
	s_barrier

.LBB0_630:
	s_add_u32 s24, s4, 0x2ff00000
	s_addc_u32 s25, s5, 0
	v_lshl_add_u64 v[0:1], v[0:1], 0, s[64:65]
	s_add_i32 m0, s10, 0x18000
	v_mov_b32_e32 v243, 0
	s_waitcnt vmcnt(2)
	s_barrier
	global_load_lds_dwordx4 v[0:1], off
	v_lshl_add_u64 v[0:1], v[2:3], 0, s[64:65]
	s_add_i32 m0, s10, 0x1a000
	s_add_i32 s26, s10, 0x8000
	s_add_i32 s27, s10, 0xa000
	global_load_lds_dwordx4 v[0:1], off
	v_lshl_add_u64 v[0:1], v[4:5], 0, s[64:65]
	s_mov_b32 m0, s26
	s_add_u32 s30, s82, 0x20080
	global_load_lds_dwordx4 v[0:1], off
	v_lshl_add_u64 v[0:1], v[6:7], 0, s[64:65]
	s_mov_b32 m0, s27
	s_addc_u32 s31, s83, 0
	global_load_lds_dwordx4 v[0:1], off
	v_lshl_add_u64 v[0:1], s[30:31], 0, v[96:97]
	s_add_i32 m0, s10, 0x1c000
	v_and_b32_e32 v15, 15, v14
	global_load_lds_dwordx4 v[0:1], off
	v_lshl_add_u64 v[0:1], s[30:31], 0, v[130:131]
	s_add_i32 m0, s10, 0x1e000
	v_readlane_b32 s6, v251, 46
	global_load_lds_dwordx4 v[0:1], off
	v_lshlrev_b32_e32 v0, 13, v11
	v_lshrrev_b32_e32 v16, 1, v14
	v_and_b32_e32 v0, 0xffffc000, v0
	v_or_b32_e32 v141, s6, v15
	v_and_b32_e32 v16, 24, v16
	v_lshl_add_u32 v0, v12, 10, v0
	v_and_b32_e32 v1, 1, v11
	v_lshlrev_b32_e32 v17, 6, v141
	v_lshlrev_b32_e32 v18, 1, v16
	s_movk_i32 s6, 0x3c0
	v_lshlrev_b32_e32 v19, 2, v141
	v_lshl_or_b32 v0, v1, 6, v0
	v_and_or_b32 v17, v17, s6, v18
	v_and_b32_e32 v19, 32, v19
	v_readlane_b32 s6, v251, 47
	v_lshlrev_b32_e32 v14, 2, v14
	v_lshl_add_u32 v136, v13, 1, v0
	v_lshlrev_b32_e32 v0, 13, v8
	v_bitop3_b32 v17, v17, s6, v19 bitop3:0xde
	v_lshl_or_b32 v15, v15, 6, v18
	v_and_b32_e32 v14, 32, v14
	v_readlane_b32 s6, v251, 49
	v_and_b32_e32 v0, 0xffffc000, v0
	s_waitcnt vmcnt(6)
	v_lshl_add_u32 v0, v9, 10, v0
	v_bitop3_b32 v142, v15, s6, v14 bitop3:0xde
	v_readlane_b32 s6, v251, 48
	v_and_b32_e32 v1, 1, v8
	v_lshl_or_b32 v0, v1, 6, v0
	v_or_b32_e32 v143, s6, v16
	v_readlane_b32 s6, v252, 63
	v_mov_b32_e32 v137, v97
	v_lshl_add_u32 v138, v10, 1, v0
	v_mov_b32_e32 v139, v97
	s_mov_b32 s28, 0
	v_add_u32_e32 v144, 0, v17
	v_readlane_b32 s33, v252, 41
	s_mov_b32 s34, s6
	s_barrier
	v_readlane_b32 s7, v250, 0
	s_branch .LBB0_633

.LBB0_636:
	s_add_u32 s56, s68, 0xfffe0080
	s_addc_u32 s57, s69, -1
	s_add_i32 s58, 0, 0x10000
	s_cmp_eq_u32 s55, 4
	s_cselect_b32 s85, s35, s57
	s_cselect_b32 s84, s43, s56
	v_add_u32_e32 v145, s58, v142
	s_cselect_b32 s83, s31, s54
	s_cselect_b32 s82, s50, s51
	s_add_i32 s59, 0, 0x14000
	ds_read_b128 v[146:149], v145
	ds_read_b128 v[150:153], v145 offset:1024
	ds_read_b128 v[158:161], v145 offset:2048
	ds_read_b128 v[162:165], v145 offset:3072
	v_add_u32_e32 v145, s59, v142
	ds_read_b128 v[166:169], v145
	ds_read_b128 v[170:173], v145 offset:1024
	ds_read_b128 v[174:177], v145 offset:2048
	ds_read_b128 v[178:181], v145 offset:3072
	v_lshl_add_u64 v[154:155], s[68:69], 0, v[136:137]
	s_add_i32 m0, s10, 0xc000
	ds_read_b128 v[182:185], v144
	ds_read_b128 v[186:189], v144 offset:1024
	ds_read_b128 v[190:193], v144 offset:2048
	ds_read_b128 v[194:197], v144 offset:3072
	ds_read_b128 v[210:213], v144 offset:4096
	ds_read_b128 v[214:217], v144 offset:5120
	ds_read_b128 v[218:221], v144 offset:6144
	ds_read_b128 v[222:225], v144 offset:7168
	global_load_lds_dwordx4 v[154:155], off
	v_lshl_add_u64 v[154:155], s[68:69], 0, v[138:139]
	s_add_i32 m0, s10, 0xe000
	s_nop 0
	global_load_lds_dwordx4 v[154:155], off
	v_cmp_ne_u32_e32 vcc, 0, v243
	s_cbranch_vccnz .Lrx_uq_0
	s_waitcnt vmcnt(8)
.Lrx_uq_0:
	s_waitcnt vmcnt(24)
	s_waitcnt lgkmcnt(0)
	s_setprio 1
	s_barrier
	v_mfma_f32_16x16x32_bf16 v[126:129], v[146:149], v[182:185], v[126:129]
	v_mfma_f32_16x16x32_bf16 v[122:125], v[158:161], v[182:185], v[122:125]
	v_mfma_f32_16x16x32_bf16 v[118:121], v[146:149], v[190:193], v[118:121]
	v_mfma_f32_16x16x32_bf16 v[114:117], v[158:161], v[190:193], v[114:117]
	v_mfma_f32_16x16x32_bf16 v[102:105], v[146:149], v[210:213], v[102:105]
	v_mfma_f32_16x16x32_bf16 v[98:101], v[158:161], v[210:213], v[98:101]
	v_mfma_f32_16x16x32_bf16 v[84:87], v[146:149], v[218:221], v[84:87]
	v_mfma_f32_16x16x32_bf16 v[80:83], v[158:161], v[218:221], v[80:83]
	v_mfma_f32_16x16x32_bf16 v[126:129], v[150:153], v[186:189], v[126:129]
	v_mfma_f32_16x16x32_bf16 v[122:125], v[162:165], v[186:189], v[122:125]
	v_mfma_f32_16x16x32_bf16 v[118:121], v[150:153], v[194:197], v[118:121]
	v_mfma_f32_16x16x32_bf16 v[114:117], v[162:165], v[194:197], v[114:117]
	v_mfma_f32_16x16x32_bf16 v[102:105], v[150:153], v[214:217], v[102:105]
	v_mfma_f32_16x16x32_bf16 v[98:101], v[162:165], v[214:217], v[98:101]
	v_mfma_f32_16x16x32_bf16 v[84:87], v[150:153], v[222:225], v[84:87]
	v_mfma_f32_16x16x32_bf16 v[80:83], v[162:165], v[222:225], v[80:83]
	v_mfma_f32_16x16x32_bf16 v[110:113], v[166:169], v[182:185], v[110:113]
	v_mfma_f32_16x16x32_bf16 v[106:109], v[174:177], v[182:185], v[106:109]
	v_mfma_f32_16x16x32_bf16 v[92:95], v[166:169], v[190:193], v[92:95]
	v_mfma_f32_16x16x32_bf16 v[88:91], v[174:177], v[190:193], v[88:91]
	v_mfma_f32_16x16x32_bf16 v[76:79], v[166:169], v[210:213], v[76:79]
	v_mfma_f32_16x16x32_bf16 v[72:75], v[174:177], v[210:213], v[72:75]
	v_mfma_f32_16x16x32_bf16 v[68:71], v[166:169], v[218:221], v[68:71]
	v_mfma_f32_16x16x32_bf16 v[64:67], v[174:177], v[218:221], v[64:67]
	v_mfma_f32_16x16x32_bf16 v[110:113], v[170:173], v[186:189], v[110:113]
	v_mfma_f32_16x16x32_bf16 v[106:109], v[178:181], v[186:189], v[106:109]
	v_mfma_f32_16x16x32_bf16 v[92:95], v[170:173], v[194:197], v[92:95]
	v_mfma_f32_16x16x32_bf16 v[88:91], v[178:181], v[194:197], v[88:91]
	v_mfma_f32_16x16x32_bf16 v[76:79], v[170:173], v[214:217], v[76:79]
	v_mfma_f32_16x16x32_bf16 v[72:75], v[178:181], v[214:217], v[72:75]
	v_mfma_f32_16x16x32_bf16 v[68:71], v[170:173], v[222:225], v[68:71]
	v_mfma_f32_16x16x32_bf16 v[64:67], v[178:181], v[222:225], v[64:67]
	s_barrier
	s_setprio 0
	s_add_i32 s56, s58, s75
	v_lshl_add_u64 v[154:155], s[82:83], 0, v[96:97]
	s_mov_b32 m0, s56
	ds_read_b128 v[182:185], v144 offset:16384
	ds_read_b128 v[186:189], v144 offset:17408
	ds_read_b128 v[190:193], v144 offset:18432
	ds_read_b128 v[194:197], v144 offset:19456
	ds_read_b128 v[210:213], v144 offset:20480
	ds_read_b128 v[214:217], v144 offset:21504
	ds_read_b128 v[218:221], v144 offset:22528
	ds_read_b128 v[222:225], v144 offset:23552
	global_load_lds_dwordx4 v[154:155], off
	s_add_i32 m0, s56, 0x2000
	s_add_u32 s56, s82, 0x20000
	v_lshl_add_u64 v[156:157], s[82:83], 0, v[130:131]
	s_addc_u32 s57, s83, 0
	s_add_i32 s58, s59, s75
	global_load_lds_dwordx4 v[156:157], off
	v_lshl_add_u64 v[198:199], s[56:57], 0, v[96:97]
	s_mov_b32 m0, s58
	v_lshl_add_u64 v[202:203], s[84:85], 0, v[132:133]
	global_load_lds_dwordx4 v[198:199], off
	v_lshl_add_u64 v[198:199], s[56:57], 0, v[130:131]
	s_add_i32 m0, s58, 0x2000
	s_nop 0
	global_load_lds_dwordx4 v[198:199], off
	v_lshl_add_u64 v[198:199], s[84:85], 0, v[134:135]
	s_mov_b32 m0, s10
	s_nop 0
	global_load_lds_dwordx4 v[198:199], off
	s_mov_b32 m0, s12
	s_nop 0
	global_load_lds_dwordx4 v[202:203], off
	v_cmp_ne_u32_e32 vcc, 0, v243
	s_cbranch_vccnz .Lrx_uq_1
	s_waitcnt vmcnt(8)
.Lrx_uq_1:
	s_waitcnt vmcnt(24)
	v_mov_b32_e32 v243, 0
	s_waitcnt lgkmcnt(0)
	s_setprio 1
	s_barrier
	v_mfma_f32_16x16x32_bf16 v[60:63], v[146:149], v[182:185], v[60:63]
	v_mfma_f32_16x16x32_bf16 v[56:59], v[158:161], v[182:185], v[56:59]
	v_mfma_f32_16x16x32_bf16 v[52:55], v[146:149], v[190:193], v[52:55]
	v_mfma_f32_16x16x32_bf16 v[48:51], v[158:161], v[190:193], v[48:51]
	v_mfma_f32_16x16x32_bf16 v[36:39], v[146:149], v[210:213], v[36:39]
	v_mfma_f32_16x16x32_bf16 v[32:35], v[158:161], v[210:213], v[32:35]
	v_mfma_f32_16x16x32_bf16 v[20:23], v[146:149], v[218:221], v[20:23]
	v_mfma_f32_16x16x32_bf16 v[16:19], v[158:161], v[218:221], v[16:19]
	v_mfma_f32_16x16x32_bf16 v[60:63], v[150:153], v[186:189], v[60:63]
	v_mfma_f32_16x16x32_bf16 v[56:59], v[162:165], v[186:189], v[56:59]
	v_mfma_f32_16x16x32_bf16 v[52:55], v[150:153], v[194:197], v[52:55]
	v_mfma_f32_16x16x32_bf16 v[48:51], v[162:165], v[194:197], v[48:51]
	v_mfma_f32_16x16x32_bf16 v[36:39], v[150:153], v[214:217], v[36:39]
	v_mfma_f32_16x16x32_bf16 v[32:35], v[162:165], v[214:217], v[32:35]
	v_mfma_f32_16x16x32_bf16 v[20:23], v[150:153], v[222:225], v[20:23]
	v_mfma_f32_16x16x32_bf16 v[16:19], v[162:165], v[222:225], v[16:19]
	v_mfma_f32_16x16x32_bf16 v[44:47], v[166:169], v[182:185], v[44:47]
	v_mfma_f32_16x16x32_bf16 v[40:43], v[174:177], v[182:185], v[40:43]
	v_mfma_f32_16x16x32_bf16 v[28:31], v[166:169], v[190:193], v[28:31]
	v_mfma_f32_16x16x32_bf16 v[24:27], v[174:177], v[190:193], v[24:27]
	v_mfma_f32_16x16x32_bf16 v[12:15], v[166:169], v[210:213], v[12:15]
	v_mfma_f32_16x16x32_bf16 v[8:11], v[174:177], v[210:213], v[8:11]
	v_mfma_f32_16x16x32_bf16 v[4:7], v[166:169], v[218:221], v[4:7]
	v_mfma_f32_16x16x32_bf16 v[0:3], v[174:177], v[218:221], v[0:3]
	v_mfma_f32_16x16x32_bf16 v[44:47], v[170:173], v[186:189], v[44:47]
	v_mfma_f32_16x16x32_bf16 v[40:43], v[178:181], v[186:189], v[40:43]
	v_mfma_f32_16x16x32_bf16 v[28:31], v[170:173], v[194:197], v[28:31]
	v_mfma_f32_16x16x32_bf16 v[24:27], v[178:181], v[194:197], v[24:27]
	v_mfma_f32_16x16x32_bf16 v[12:15], v[170:173], v[214:217], v[12:15]
	v_mfma_f32_16x16x32_bf16 v[8:11], v[178:181], v[214:217], v[8:11]
	v_mfma_f32_16x16x32_bf16 v[4:7], v[170:173], v[222:225], v[4:7]
	v_mfma_f32_16x16x32_bf16 v[0:3], v[178:181], v[222:225], v[0:3]
	s_barrier
	s_setprio 0
	s_add_i32 s58, 0, 0x18000
	v_add_u32_e32 v145, s58, v142
	s_add_i32 s59, 0, 0x1c000
	ds_read_b128 v[146:149], v145
	ds_read_b128 v[150:153], v145 offset:1024
	ds_read_b128 v[158:161], v145 offset:2048
	ds_read_b128 v[162:165], v145 offset:3072
	v_add_u32_e32 v145, s59, v142
	ds_read_b128 v[166:169], v145
	ds_read_b128 v[170:173], v145 offset:1024
	ds_read_b128 v[174:177], v145 offset:2048
	ds_read_b128 v[178:181], v145 offset:3072
	s_add_u32 s56, s84, 0x20000
	s_addc_u32 s57, s85, 0
	s_mov_b32 m0, s18
	v_lshl_add_u64 v[204:205], s[56:57], 0, v[134:135]
	ds_read_b128 v[182:185], v144 offset:32768
	ds_read_b128 v[186:189], v144 offset:33792
	ds_read_b128 v[190:193], v144 offset:34816
	ds_read_b128 v[194:197], v144 offset:35840
	ds_read_b128 v[210:213], v144 offset:36864
	ds_read_b128 v[214:217], v144 offset:37888
	ds_read_b128 v[218:221], v144 offset:38912
	ds_read_b128 v[222:225], v144 offset:39936
	global_load_lds_dwordx4 v[204:205], off
	v_lshl_add_u64 v[204:205], s[56:57], 0, v[132:133]
	s_mov_b32 m0, s20
	s_nop 0
	global_load_lds_dwordx4 v[204:205], off
	s_waitcnt vmcnt(8)
	s_waitcnt lgkmcnt(0)
	s_setprio 1
	s_barrier
	v_mfma_f32_16x16x32_bf16 v[126:129], v[146:149], v[182:185], v[126:129]
	v_mfma_f32_16x16x32_bf16 v[122:125], v[158:161], v[182:185], v[122:125]
	v_mfma_f32_16x16x32_bf16 v[118:121], v[146:149], v[190:193], v[118:121]
	v_mfma_f32_16x16x32_bf16 v[114:117], v[158:161], v[190:193], v[114:117]
	v_mfma_f32_16x16x32_bf16 v[102:105], v[146:149], v[210:213], v[102:105]
	v_mfma_f32_16x16x32_bf16 v[98:101], v[158:161], v[210:213], v[98:101]
	v_mfma_f32_16x16x32_bf16 v[84:87], v[146:149], v[218:221], v[84:87]
	v_mfma_f32_16x16x32_bf16 v[80:83], v[158:161], v[218:221], v[80:83]
	v_mfma_f32_16x16x32_bf16 v[126:129], v[150:153], v[186:189], v[126:129]
	v_mfma_f32_16x16x32_bf16 v[122:125], v[162:165], v[186:189], v[122:125]
	v_mfma_f32_16x16x32_bf16 v[118:121], v[150:153], v[194:197], v[118:121]
	v_mfma_f32_16x16x32_bf16 v[114:117], v[162:165], v[194:197], v[114:117]
	v_mfma_f32_16x16x32_bf16 v[102:105], v[150:153], v[214:217], v[102:105]
	v_mfma_f32_16x16x32_bf16 v[98:101], v[162:165], v[214:217], v[98:101]
	v_mfma_f32_16x16x32_bf16 v[84:87], v[150:153], v[222:225], v[84:87]
	v_mfma_f32_16x16x32_bf16 v[80:83], v[162:165], v[222:225], v[80:83]
	v_mfma_f32_16x16x32_bf16 v[110:113], v[166:169], v[182:185], v[110:113]
	v_mfma_f32_16x16x32_bf16 v[106:109], v[174:177], v[182:185], v[106:109]
	v_mfma_f32_16x16x32_bf16 v[92:95], v[166:169], v[190:193], v[92:95]
	v_mfma_f32_16x16x32_bf16 v[88:91], v[174:177], v[190:193], v[88:91]
	v_mfma_f32_16x16x32_bf16 v[76:79], v[166:169], v[210:213], v[76:79]
	v_mfma_f32_16x16x32_bf16 v[72:75], v[174:177], v[210:213], v[72:75]
	v_mfma_f32_16x16x32_bf16 v[68:71], v[166:169], v[218:221], v[68:71]
	v_mfma_f32_16x16x32_bf16 v[64:67], v[174:177], v[218:221], v[64:67]
	v_mfma_f32_16x16x32_bf16 v[110:113], v[170:173], v[186:189], v[110:113]
	v_mfma_f32_16x16x32_bf16 v[106:109], v[178:181], v[186:189], v[106:109]
	v_mfma_f32_16x16x32_bf16 v[92:95], v[170:173], v[194:197], v[92:95]
	v_mfma_f32_16x16x32_bf16 v[88:91], v[178:181], v[194:197], v[88:91]
	v_mfma_f32_16x16x32_bf16 v[76:79], v[170:173], v[214:217], v[76:79]
	v_mfma_f32_16x16x32_bf16 v[72:75], v[178:181], v[214:217], v[72:75]
	v_mfma_f32_16x16x32_bf16 v[68:71], v[170:173], v[222:225], v[68:71]
	v_mfma_f32_16x16x32_bf16 v[64:67], v[178:181], v[222:225], v[64:67]
	s_barrier
	s_setprio 0
	s_add_i32 s56, s58, s75
	v_lshl_add_u64 v[154:155], v[154:155], 0, s[64:65]
	s_mov_b32 m0, s56
	ds_read_b128 v[182:185], v144 offset:49152
	ds_read_b128 v[186:189], v144 offset:50176
	ds_read_b128 v[190:193], v144 offset:51200
	ds_read_b128 v[194:197], v144 offset:52224
	ds_read_b128 v[210:213], v144 offset:53248
	ds_read_b128 v[214:217], v144 offset:54272
	ds_read_b128 v[218:221], v144 offset:55296
	ds_read_b128 v[222:225], v144 offset:56320
	global_load_lds_dwordx4 v[154:155], off
	s_add_i32 m0, s56, 0x2000
	s_add_u32 s56, s82, 0x20080
	v_lshl_add_u64 v[154:155], v[156:157], 0, s[64:65]
	s_addc_u32 s57, s83, 0
	s_add_i32 s58, s59, s75
	global_load_lds_dwordx4 v[154:155], off
	v_lshl_add_u64 v[154:155], s[56:57], 0, v[96:97]
	s_mov_b32 m0, s58
	s_nop 0
	global_load_lds_dwordx4 v[154:155], off
	v_lshl_add_u64 v[154:155], s[56:57], 0, v[130:131]
	s_add_i32 m0, s58, 0x2000
	s_nop 0
	global_load_lds_dwordx4 v[154:155], off
	v_lshl_add_u64 v[154:155], v[198:199], 0, s[64:65]
	s_mov_b32 m0, s26
	s_nop 0
	global_load_lds_dwordx4 v[154:155], off
	v_lshl_add_u64 v[154:155], v[202:203], 0, s[64:65]
	s_mov_b32 m0, s27
	s_nop 0
	global_load_lds_dwordx4 v[154:155], off
	s_waitcnt vmcnt(8)
	s_waitcnt lgkmcnt(0)
	s_setprio 1
	s_barrier
	v_mfma_f32_16x16x32_bf16 v[60:63], v[146:149], v[182:185], v[60:63]
	v_mfma_f32_16x16x32_bf16 v[56:59], v[158:161], v[182:185], v[56:59]
	v_mfma_f32_16x16x32_bf16 v[52:55], v[146:149], v[190:193], v[52:55]
	v_mfma_f32_16x16x32_bf16 v[48:51], v[158:161], v[190:193], v[48:51]
	v_mfma_f32_16x16x32_bf16 v[36:39], v[146:149], v[210:213], v[36:39]
	v_mfma_f32_16x16x32_bf16 v[32:35], v[158:161], v[210:213], v[32:35]
	v_mfma_f32_16x16x32_bf16 v[20:23], v[146:149], v[218:221], v[20:23]
	v_mfma_f32_16x16x32_bf16 v[16:19], v[158:161], v[218:221], v[16:19]
	v_mfma_f32_16x16x32_bf16 v[60:63], v[150:153], v[186:189], v[60:63]
	v_mfma_f32_16x16x32_bf16 v[56:59], v[162:165], v[186:189], v[56:59]
	v_mfma_f32_16x16x32_bf16 v[52:55], v[150:153], v[194:197], v[52:55]
	v_mfma_f32_16x16x32_bf16 v[48:51], v[162:165], v[194:197], v[48:51]
	v_mfma_f32_16x16x32_bf16 v[36:39], v[150:153], v[214:217], v[36:39]
	v_mfma_f32_16x16x32_bf16 v[32:35], v[162:165], v[214:217], v[32:35]
	v_mfma_f32_16x16x32_bf16 v[20:23], v[150:153], v[222:225], v[20:23]
	v_mfma_f32_16x16x32_bf16 v[16:19], v[162:165], v[222:225], v[16:19]
	v_mfma_f32_16x16x32_bf16 v[44:47], v[166:169], v[182:185], v[44:47]
	v_mfma_f32_16x16x32_bf16 v[40:43], v[174:177], v[182:185], v[40:43]
	v_mfma_f32_16x16x32_bf16 v[28:31], v[166:169], v[190:193], v[28:31]
	v_mfma_f32_16x16x32_bf16 v[24:27], v[174:177], v[190:193], v[24:27]
	v_mfma_f32_16x16x32_bf16 v[12:15], v[166:169], v[210:213], v[12:15]
	v_mfma_f32_16x16x32_bf16 v[8:11], v[174:177], v[210:213], v[8:11]
	v_mfma_f32_16x16x32_bf16 v[4:7], v[166:169], v[218:221], v[4:7]
	v_mfma_f32_16x16x32_bf16 v[0:3], v[174:177], v[218:221], v[0:3]
	v_mfma_f32_16x16x32_bf16 v[44:47], v[170:173], v[186:189], v[44:47]
	v_mfma_f32_16x16x32_bf16 v[40:43], v[178:181], v[186:189], v[40:43]
	v_mfma_f32_16x16x32_bf16 v[28:31], v[170:173], v[194:197], v[28:31]
	v_mfma_f32_16x16x32_bf16 v[24:27], v[178:181], v[194:197], v[24:27]
	v_mfma_f32_16x16x32_bf16 v[12:15], v[170:173], v[214:217], v[12:15]
	v_mfma_f32_16x16x32_bf16 v[8:11], v[178:181], v[214:217], v[8:11]
	v_mfma_f32_16x16x32_bf16 v[4:7], v[170:173], v[222:225], v[4:7]
	v_mfma_f32_16x16x32_bf16 v[0:3], v[178:181], v[222:225], v[0:3]
	s_barrier
	s_setprio 0
	s_add_i32 s55, s55, 2
	s_add_u32 s68, s68, 0x100
	s_addc_u32 s69, s69, 0
	s_add_u32 s51, s51, 0x100
	s_addc_u32 s54, s54, 0
	s_cmp_gt_u32 s55, 5
	s_cbranch_scc0 .LBB0_636
	v_mov_b32_e32 v243, 1
	v_readlane_b32 s6, v251, 54
	v_readlane_b32 s7, v251, 55
	s_and_b64 vcc, exec, s[6:7]
	s_cbranch_vccz .LBB0_639
	s_barrier

.LBB0_646:
	s_add_u32 s24, s4, 0x33000000
	s_addc_u32 s25, s5, 0
	v_lshl_add_u64 v[0:1], v[0:1], 0, s[64:65]
	s_add_i32 m0, s18, 0x18000
	v_mov_b32_e32 v243, 0
	s_waitcnt vmcnt(2)
	s_barrier
	global_load_lds_dwordx4 v[0:1], off
	v_lshl_add_u64 v[0:1], v[2:3], 0, s[64:65]
	s_add_i32 m0, s18, 0x1a000
	s_add_i32 s28, s18, 0x8000
	s_add_i32 s33, s18, 0xa000
	global_load_lds_dwordx4 v[0:1], off
	v_lshl_add_u64 v[0:1], v[4:5], 0, s[64:65]
	s_mov_b32 m0, s28
	s_add_u32 s30, s82, 0x20080
	global_load_lds_dwordx4 v[0:1], off
	v_lshl_add_u64 v[0:1], v[6:7], 0, s[64:65]
	s_mov_b32 m0, s33
	s_addc_u32 s31, s83, 0
	global_load_lds_dwordx4 v[0:1], off
	v_lshl_add_u64 v[0:1], s[30:31], 0, v[96:97]
	s_add_i32 m0, s18, 0x1c000
	v_and_b32_e32 v15, 15, v14
	global_load_lds_dwordx4 v[0:1], off
	v_lshl_add_u64 v[0:1], s[30:31], 0, v[130:131]
	s_add_i32 m0, s18, 0x1e000
	v_readlane_b32 s6, v251, 46
	global_load_lds_dwordx4 v[0:1], off
	v_lshlrev_b32_e32 v0, 13, v11
	v_lshrrev_b32_e32 v16, 1, v14
	v_and_b32_e32 v0, 0xffffc000, v0
	v_or_b32_e32 v141, s6, v15
	v_and_b32_e32 v16, 24, v16
	v_lshl_add_u32 v0, v12, 10, v0
	v_and_b32_e32 v1, 1, v11
	v_lshlrev_b32_e32 v17, 6, v141
	v_lshlrev_b32_e32 v18, 1, v16
	s_movk_i32 s6, 0x3c0
	v_lshlrev_b32_e32 v19, 2, v141
	v_lshl_or_b32 v0, v1, 6, v0
	v_and_or_b32 v17, v17, s6, v18
	v_and_b32_e32 v19, 32, v19
	v_readlane_b32 s6, v251, 47
	v_lshlrev_b32_e32 v14, 2, v14
	v_lshl_add_u32 v136, v13, 1, v0
	v_lshlrev_b32_e32 v0, 13, v8
	v_bitop3_b32 v17, v17, s6, v19 bitop3:0xde
	v_lshl_or_b32 v15, v15, 6, v18
	v_and_b32_e32 v14, 32, v14
	v_readlane_b32 s6, v251, 49
	v_and_b32_e32 v0, 0xffffc000, v0
	s_waitcnt vmcnt(6)
	v_lshl_add_u32 v0, v9, 10, v0
	v_bitop3_b32 v142, v15, s6, v14 bitop3:0xde
	v_readlane_b32 s6, v251, 48
	v_and_b32_e32 v1, 1, v8
	v_lshl_or_b32 v0, v1, 6, v0
	v_or_b32_e32 v143, s6, v16
	v_readlane_b32 s6, v250, 15
	v_mov_b32_e32 v137, v97
	v_lshl_add_u32 v138, v10, 1, v0
	v_mov_b32_e32 v139, v97
	s_mov_b32 s34, 0
	v_add_u32_e32 v144, 0, v17
	v_readlane_b32 s35, v252, 44
	s_mov_b32 s50, s6
	s_barrier
	v_readlane_b32 s7, v250, 16
	s_branch .LBB0_649

.LBB0_656:
	s_add_u32 s58, s68, 0xfffe0080
	s_addc_u32 s59, s69, -1
	s_add_i32 s61, 0, 0x10000
	s_cmp_eq_u32 s57, 4
	s_cselect_b32 s85, s43, s59
	s_cselect_b32 s84, s51, s58
	v_add_u32_e32 v145, s61, v142
	s_cselect_b32 s83, s31, s56
	s_cselect_b32 s82, s54, s55
	s_add_i32 s62, 0, 0x14000
	ds_read_b128 v[146:149], v145
	ds_read_b128 v[150:153], v145 offset:1024
	ds_read_b128 v[158:161], v145 offset:2048
	ds_read_b128 v[162:165], v145 offset:3072
	v_add_u32_e32 v145, s62, v142
	ds_read_b128 v[166:169], v145
	ds_read_b128 v[170:173], v145 offset:1024
	ds_read_b128 v[174:177], v145 offset:2048
	ds_read_b128 v[178:181], v145 offset:3072
	v_lshl_add_u64 v[154:155], s[68:69], 0, v[136:137]
	s_add_i32 m0, s18, 0xc000
	ds_read_b128 v[182:185], v144
	ds_read_b128 v[186:189], v144 offset:1024
	ds_read_b128 v[190:193], v144 offset:2048
	ds_read_b128 v[194:197], v144 offset:3072
	ds_read_b128 v[210:213], v144 offset:4096
	ds_read_b128 v[214:217], v144 offset:5120
	ds_read_b128 v[218:221], v144 offset:6144
	ds_read_b128 v[222:225], v144 offset:7168
	global_load_lds_dwordx4 v[154:155], off
	v_lshl_add_u64 v[154:155], s[68:69], 0, v[138:139]
	s_add_i32 m0, s18, 0xe000
	s_nop 0
	global_load_lds_dwordx4 v[154:155], off
	v_cmp_ne_u32_e32 vcc, 0, v243
	s_cbranch_vccnz .Lrx_ukv_0
	s_waitcnt vmcnt(8)
.Lrx_ukv_0:
	s_waitcnt vmcnt(24)
	s_waitcnt lgkmcnt(0)
	s_setprio 1
	s_barrier
	v_mfma_f32_16x16x32_bf16 v[126:129], v[146:149], v[182:185], v[126:129]
	v_mfma_f32_16x16x32_bf16 v[122:125], v[158:161], v[182:185], v[122:125]
	v_mfma_f32_16x16x32_bf16 v[118:121], v[146:149], v[190:193], v[118:121]
	v_mfma_f32_16x16x32_bf16 v[114:117], v[158:161], v[190:193], v[114:117]
	v_mfma_f32_16x16x32_bf16 v[102:105], v[146:149], v[210:213], v[102:105]
	v_mfma_f32_16x16x32_bf16 v[98:101], v[158:161], v[210:213], v[98:101]
	v_mfma_f32_16x16x32_bf16 v[84:87], v[146:149], v[218:221], v[84:87]
	v_mfma_f32_16x16x32_bf16 v[80:83], v[158:161], v[218:221], v[80:83]
	v_mfma_f32_16x16x32_bf16 v[126:129], v[150:153], v[186:189], v[126:129]
	v_mfma_f32_16x16x32_bf16 v[122:125], v[162:165], v[186:189], v[122:125]
	v_mfma_f32_16x16x32_bf16 v[118:121], v[150:153], v[194:197], v[118:121]
	v_mfma_f32_16x16x32_bf16 v[114:117], v[162:165], v[194:197], v[114:117]
	v_mfma_f32_16x16x32_bf16 v[102:105], v[150:153], v[214:217], v[102:105]
	v_mfma_f32_16x16x32_bf16 v[98:101], v[162:165], v[214:217], v[98:101]
	v_mfma_f32_16x16x32_bf16 v[84:87], v[150:153], v[222:225], v[84:87]
	v_mfma_f32_16x16x32_bf16 v[80:83], v[162:165], v[222:225], v[80:83]
	v_mfma_f32_16x16x32_bf16 v[110:113], v[166:169], v[182:185], v[110:113]
	v_mfma_f32_16x16x32_bf16 v[106:109], v[174:177], v[182:185], v[106:109]
	v_mfma_f32_16x16x32_bf16 v[92:95], v[166:169], v[190:193], v[92:95]
	v_mfma_f32_16x16x32_bf16 v[88:91], v[174:177], v[190:193], v[88:91]
	v_mfma_f32_16x16x32_bf16 v[76:79], v[166:169], v[210:213], v[76:79]
	v_mfma_f32_16x16x32_bf16 v[72:75], v[174:177], v[210:213], v[72:75]
	v_mfma_f32_16x16x32_bf16 v[68:71], v[166:169], v[218:221], v[68:71]
	v_mfma_f32_16x16x32_bf16 v[64:67], v[174:177], v[218:221], v[64:67]
	v_mfma_f32_16x16x32_bf16 v[110:113], v[170:173], v[186:189], v[110:113]
	v_mfma_f32_16x16x32_bf16 v[106:109], v[178:181], v[186:189], v[106:109]
	v_mfma_f32_16x16x32_bf16 v[92:95], v[170:173], v[194:197], v[92:95]
	v_mfma_f32_16x16x32_bf16 v[88:91], v[178:181], v[194:197], v[88:91]
	v_mfma_f32_16x16x32_bf16 v[76:79], v[170:173], v[214:217], v[76:79]
	v_mfma_f32_16x16x32_bf16 v[72:75], v[178:181], v[214:217], v[72:75]
	v_mfma_f32_16x16x32_bf16 v[68:71], v[170:173], v[222:225], v[68:71]
	v_mfma_f32_16x16x32_bf16 v[64:67], v[178:181], v[222:225], v[64:67]
	s_barrier
	s_setprio 0
	s_add_i32 s58, s61, s75
	v_lshl_add_u64 v[154:155], s[82:83], 0, v[96:97]
	s_mov_b32 m0, s58
	ds_read_b128 v[182:185], v144 offset:16384
	ds_read_b128 v[186:189], v144 offset:17408
	ds_read_b128 v[190:193], v144 offset:18432
	ds_read_b128 v[194:197], v144 offset:19456
	ds_read_b128 v[210:213], v144 offset:20480
	ds_read_b128 v[214:217], v144 offset:21504
	ds_read_b128 v[218:221], v144 offset:22528
	ds_read_b128 v[222:225], v144 offset:23552
	global_load_lds_dwordx4 v[154:155], off
	s_add_i32 m0, s58, 0x2000
	s_add_u32 s58, s82, 0x20000
	v_lshl_add_u64 v[156:157], s[82:83], 0, v[130:131]
	s_addc_u32 s59, s83, 0
	s_add_i32 s61, s62, s75
	global_load_lds_dwordx4 v[156:157], off
	v_lshl_add_u64 v[198:199], s[58:59], 0, v[96:97]
	s_mov_b32 m0, s61
	v_lshl_add_u64 v[202:203], s[84:85], 0, v[132:133]
	global_load_lds_dwordx4 v[198:199], off
	v_lshl_add_u64 v[198:199], s[58:59], 0, v[130:131]
	s_add_i32 m0, s61, 0x2000
	s_nop 0
	global_load_lds_dwordx4 v[198:199], off
	v_lshl_add_u64 v[198:199], s[84:85], 0, v[134:135]
	s_mov_b32 m0, s18
	s_nop 0
	global_load_lds_dwordx4 v[198:199], off
	s_mov_b32 m0, s20
	s_nop 0
	global_load_lds_dwordx4 v[202:203], off
	v_cmp_ne_u32_e32 vcc, 0, v243
	s_cbranch_vccnz .Lrx_ukv_1
	s_waitcnt vmcnt(8)
.Lrx_ukv_1:
	s_waitcnt vmcnt(24)
	v_mov_b32_e32 v243, 0
	s_waitcnt lgkmcnt(0)
	s_setprio 1
	s_barrier
	v_mfma_f32_16x16x32_bf16 v[60:63], v[146:149], v[182:185], v[60:63]
	v_mfma_f32_16x16x32_bf16 v[56:59], v[158:161], v[182:185], v[56:59]
	v_mfma_f32_16x16x32_bf16 v[52:55], v[146:149], v[190:193], v[52:55]
	v_mfma_f32_16x16x32_bf16 v[48:51], v[158:161], v[190:193], v[48:51]
	v_mfma_f32_16x16x32_bf16 v[36:39], v[146:149], v[210:213], v[36:39]
	v_mfma_f32_16x16x32_bf16 v[32:35], v[158:161], v[210:213], v[32:35]
	v_mfma_f32_16x16x32_bf16 v[20:23], v[146:149], v[218:221], v[20:23]
	v_mfma_f32_16x16x32_bf16 v[16:19], v[158:161], v[218:221], v[16:19]
	v_mfma_f32_16x16x32_bf16 v[60:63], v[150:153], v[186:189], v[60:63]
	v_mfma_f32_16x16x32_bf16 v[56:59], v[162:165], v[186:189], v[56:59]
	v_mfma_f32_16x16x32_bf16 v[52:55], v[150:153], v[194:197], v[52:55]
	v_mfma_f32_16x16x32_bf16 v[48:51], v[162:165], v[194:197], v[48:51]
	v_mfma_f32_16x16x32_bf16 v[36:39], v[150:153], v[214:217], v[36:39]
	v_mfma_f32_16x16x32_bf16 v[32:35], v[162:165], v[214:217], v[32:35]
	v_mfma_f32_16x16x32_bf16 v[20:23], v[150:153], v[222:225], v[20:23]
	v_mfma_f32_16x16x32_bf16 v[16:19], v[162:165], v[222:225], v[16:19]
	v_mfma_f32_16x16x32_bf16 v[44:47], v[166:169], v[182:185], v[44:47]
	v_mfma_f32_16x16x32_bf16 v[40:43], v[174:177], v[182:185], v[40:43]
	v_mfma_f32_16x16x32_bf16 v[28:31], v[166:169], v[190:193], v[28:31]
	v_mfma_f32_16x16x32_bf16 v[24:27], v[174:177], v[190:193], v[24:27]
	v_mfma_f32_16x16x32_bf16 v[12:15], v[166:169], v[210:213], v[12:15]
	v_mfma_f32_16x16x32_bf16 v[8:11], v[174:177], v[210:213], v[8:11]
	v_mfma_f32_16x16x32_bf16 v[4:7], v[166:169], v[218:221], v[4:7]
	v_mfma_f32_16x16x32_bf16 v[0:3], v[174:177], v[218:221], v[0:3]
	v_mfma_f32_16x16x32_bf16 v[44:47], v[170:173], v[186:189], v[44:47]
	v_mfma_f32_16x16x32_bf16 v[40:43], v[178:181], v[186:189], v[40:43]
	v_mfma_f32_16x16x32_bf16 v[28:31], v[170:173], v[194:197], v[28:31]
	v_mfma_f32_16x16x32_bf16 v[24:27], v[178:181], v[194:197], v[24:27]
	v_mfma_f32_16x16x32_bf16 v[12:15], v[170:173], v[214:217], v[12:15]
	v_mfma_f32_16x16x32_bf16 v[8:11], v[178:181], v[214:217], v[8:11]
	v_mfma_f32_16x16x32_bf16 v[4:7], v[170:173], v[222:225], v[4:7]
	v_mfma_f32_16x16x32_bf16 v[0:3], v[178:181], v[222:225], v[0:3]
	s_barrier
	s_setprio 0
	s_add_i32 s61, 0, 0x18000
	v_add_u32_e32 v145, s61, v142
	s_add_i32 s62, 0, 0x1c000
	ds_read_b128 v[146:149], v145
	ds_read_b128 v[150:153], v145 offset:1024
	ds_read_b128 v[158:161], v145 offset:2048
	ds_read_b128 v[162:165], v145 offset:3072
	v_add_u32_e32 v145, s62, v142
	ds_read_b128 v[166:169], v145
	ds_read_b128 v[170:173], v145 offset:1024
	ds_read_b128 v[174:177], v145 offset:2048
	ds_read_b128 v[178:181], v145 offset:3072
	s_add_u32 s58, s84, 0x20000
	s_addc_u32 s59, s85, 0
	s_mov_b32 m0, s26
	v_lshl_add_u64 v[204:205], s[58:59], 0, v[134:135]
	ds_read_b128 v[182:185], v144 offset:32768
	ds_read_b128 v[186:189], v144 offset:33792
	ds_read_b128 v[190:193], v144 offset:34816
	ds_read_b128 v[194:197], v144 offset:35840
	ds_read_b128 v[210:213], v144 offset:36864
	ds_read_b128 v[214:217], v144 offset:37888
	ds_read_b128 v[218:221], v144 offset:38912
	ds_read_b128 v[222:225], v144 offset:39936
	global_load_lds_dwordx4 v[204:205], off
	v_lshl_add_u64 v[204:205], s[58:59], 0, v[132:133]
	s_mov_b32 m0, s27
	s_nop 0
	global_load_lds_dwordx4 v[204:205], off
	s_waitcnt vmcnt(8)
	s_waitcnt lgkmcnt(0)
	s_setprio 1
	s_barrier
	v_mfma_f32_16x16x32_bf16 v[126:129], v[146:149], v[182:185], v[126:129]
	v_mfma_f32_16x16x32_bf16 v[122:125], v[158:161], v[182:185], v[122:125]
	v_mfma_f32_16x16x32_bf16 v[118:121], v[146:149], v[190:193], v[118:121]
	v_mfma_f32_16x16x32_bf16 v[114:117], v[158:161], v[190:193], v[114:117]
	v_mfma_f32_16x16x32_bf16 v[102:105], v[146:149], v[210:213], v[102:105]
	v_mfma_f32_16x16x32_bf16 v[98:101], v[158:161], v[210:213], v[98:101]
	v_mfma_f32_16x16x32_bf16 v[84:87], v[146:149], v[218:221], v[84:87]
	v_mfma_f32_16x16x32_bf16 v[80:83], v[158:161], v[218:221], v[80:83]
	v_mfma_f32_16x16x32_bf16 v[126:129], v[150:153], v[186:189], v[126:129]
	v_mfma_f32_16x16x32_bf16 v[122:125], v[162:165], v[186:189], v[122:125]
	v_mfma_f32_16x16x32_bf16 v[118:121], v[150:153], v[194:197], v[118:121]
	v_mfma_f32_16x16x32_bf16 v[114:117], v[162:165], v[194:197], v[114:117]
	v_mfma_f32_16x16x32_bf16 v[102:105], v[150:153], v[214:217], v[102:105]
	v_mfma_f32_16x16x32_bf16 v[98:101], v[162:165], v[214:217], v[98:101]
	v_mfma_f32_16x16x32_bf16 v[84:87], v[150:153], v[222:225], v[84:87]
	v_mfma_f32_16x16x32_bf16 v[80:83], v[162:165], v[222:225], v[80:83]
	v_mfma_f32_16x16x32_bf16 v[110:113], v[166:169], v[182:185], v[110:113]
	v_mfma_f32_16x16x32_bf16 v[106:109], v[174:177], v[182:185], v[106:109]
	v_mfma_f32_16x16x32_bf16 v[92:95], v[166:169], v[190:193], v[92:95]
	v_mfma_f32_16x16x32_bf16 v[88:91], v[174:177], v[190:193], v[88:91]
	v_mfma_f32_16x16x32_bf16 v[76:79], v[166:169], v[210:213], v[76:79]
	v_mfma_f32_16x16x32_bf16 v[72:75], v[174:177], v[210:213], v[72:75]
	v_mfma_f32_16x16x32_bf16 v[68:71], v[166:169], v[218:221], v[68:71]
	v_mfma_f32_16x16x32_bf16 v[64:67], v[174:177], v[218:221], v[64:67]
	v_mfma_f32_16x16x32_bf16 v[110:113], v[170:173], v[186:189], v[110:113]
	v_mfma_f32_16x16x32_bf16 v[106:109], v[178:181], v[186:189], v[106:109]
	v_mfma_f32_16x16x32_bf16 v[92:95], v[170:173], v[194:197], v[92:95]
	v_mfma_f32_16x16x32_bf16 v[88:91], v[178:181], v[194:197], v[88:91]
	v_mfma_f32_16x16x32_bf16 v[76:79], v[170:173], v[214:217], v[76:79]
	v_mfma_f32_16x16x32_bf16 v[72:75], v[178:181], v[214:217], v[72:75]
	v_mfma_f32_16x16x32_bf16 v[68:71], v[170:173], v[222:225], v[68:71]
	v_mfma_f32_16x16x32_bf16 v[64:67], v[178:181], v[222:225], v[64:67]
	s_barrier
	s_setprio 0
	s_add_i32 s58, s61, s75
	v_lshl_add_u64 v[154:155], v[154:155], 0, s[64:65]
	s_mov_b32 m0, s58
	ds_read_b128 v[182:185], v144 offset:49152
	ds_read_b128 v[186:189], v144 offset:50176
	ds_read_b128 v[190:193], v144 offset:51200
	ds_read_b128 v[194:197], v144 offset:52224
	ds_read_b128 v[210:213], v144 offset:53248
	ds_read_b128 v[214:217], v144 offset:54272
	ds_read_b128 v[218:221], v144 offset:55296
	ds_read_b128 v[222:225], v144 offset:56320
	global_load_lds_dwordx4 v[154:155], off
	s_add_i32 m0, s58, 0x2000
	s_add_u32 s58, s82, 0x20080
	v_lshl_add_u64 v[154:155], v[156:157], 0, s[64:65]
	s_addc_u32 s59, s83, 0
	s_add_i32 s61, s62, s75
	global_load_lds_dwordx4 v[154:155], off
	v_lshl_add_u64 v[154:155], s[58:59], 0, v[96:97]
	s_mov_b32 m0, s61
	s_nop 0
	global_load_lds_dwordx4 v[154:155], off
	v_lshl_add_u64 v[154:155], s[58:59], 0, v[130:131]
	s_add_i32 m0, s61, 0x2000
	s_nop 0
	global_load_lds_dwordx4 v[154:155], off
	v_lshl_add_u64 v[154:155], v[198:199], 0, s[64:65]
	s_mov_b32 m0, s28
	s_nop 0
	global_load_lds_dwordx4 v[154:155], off
	v_lshl_add_u64 v[154:155], v[202:203], 0, s[64:65]
	s_mov_b32 m0, s33
	s_nop 0
	global_load_lds_dwordx4 v[154:155], off
	s_waitcnt vmcnt(8)
	s_waitcnt lgkmcnt(0)
	s_setprio 1
	s_barrier
	v_mfma_f32_16x16x32_bf16 v[60:63], v[146:149], v[182:185], v[60:63]
	v_mfma_f32_16x16x32_bf16 v[56:59], v[158:161], v[182:185], v[56:59]
	v_mfma_f32_16x16x32_bf16 v[52:55], v[146:149], v[190:193], v[52:55]
	v_mfma_f32_16x16x32_bf16 v[48:51], v[158:161], v[190:193], v[48:51]
	v_mfma_f32_16x16x32_bf16 v[36:39], v[146:149], v[210:213], v[36:39]
	v_mfma_f32_16x16x32_bf16 v[32:35], v[158:161], v[210:213], v[32:35]
	v_mfma_f32_16x16x32_bf16 v[20:23], v[146:149], v[218:221], v[20:23]
	v_mfma_f32_16x16x32_bf16 v[16:19], v[158:161], v[218:221], v[16:19]
	v_mfma_f32_16x16x32_bf16 v[60:63], v[150:153], v[186:189], v[60:63]
	v_mfma_f32_16x16x32_bf16 v[56:59], v[162:165], v[186:189], v[56:59]
	v_mfma_f32_16x16x32_bf16 v[52:55], v[150:153], v[194:197], v[52:55]
	v_mfma_f32_16x16x32_bf16 v[48:51], v[162:165], v[194:197], v[48:51]
	v_mfma_f32_16x16x32_bf16 v[36:39], v[150:153], v[214:217], v[36:39]
	v_mfma_f32_16x16x32_bf16 v[32:35], v[162:165], v[214:217], v[32:35]
	v_mfma_f32_16x16x32_bf16 v[20:23], v[150:153], v[222:225], v[20:23]
	v_mfma_f32_16x16x32_bf16 v[16:19], v[162:165], v[222:225], v[16:19]
	v_mfma_f32_16x16x32_bf16 v[44:47], v[166:169], v[182:185], v[44:47]
	v_mfma_f32_16x16x32_bf16 v[40:43], v[174:177], v[182:185], v[40:43]
	v_mfma_f32_16x16x32_bf16 v[28:31], v[166:169], v[190:193], v[28:31]
	v_mfma_f32_16x16x32_bf16 v[24:27], v[174:177], v[190:193], v[24:27]
	v_mfma_f32_16x16x32_bf16 v[12:15], v[166:169], v[210:213], v[12:15]
	v_mfma_f32_16x16x32_bf16 v[8:11], v[174:177], v[210:213], v[8:11]
	v_mfma_f32_16x16x32_bf16 v[4:7], v[166:169], v[218:221], v[4:7]
	v_mfma_f32_16x16x32_bf16 v[0:3], v[174:177], v[218:221], v[0:3]
	v_mfma_f32_16x16x32_bf16 v[44:47], v[170:173], v[186:189], v[44:47]
	v_mfma_f32_16x16x32_bf16 v[40:43], v[178:181], v[186:189], v[40:43]
	v_mfma_f32_16x16x32_bf16 v[28:31], v[170:173], v[194:197], v[28:31]
	v_mfma_f32_16x16x32_bf16 v[24:27], v[178:181], v[194:197], v[24:27]
	v_mfma_f32_16x16x32_bf16 v[12:15], v[170:173], v[214:217], v[12:15]
	v_mfma_f32_16x16x32_bf16 v[8:11], v[178:181], v[214:217], v[8:11]
	v_mfma_f32_16x16x32_bf16 v[4:7], v[170:173], v[222:225], v[4:7]
	v_mfma_f32_16x16x32_bf16 v[0:3], v[178:181], v[222:225], v[0:3]
	s_barrier
	s_setprio 0
	s_add_i32 s57, s57, 2
	s_add_u32 s68, s68, 0x100
	s_addc_u32 s69, s69, 0
	s_add_u32 s55, s55, 0x100
	s_addc_u32 s56, s56, 0
	s_cmp_gt_u32 s57, 5
	s_cbranch_scc0 .LBB0_656
	v_mov_b32_e32 v243, 1
	v_readlane_b32 s6, v251, 54
	v_readlane_b32 s7, v251, 55
	s_and_b64 vcc, exec, s[6:7]
	s_cbranch_vccz .LBB0_659
	s_barrier

.LBB0_1028:
	v_readlane_b32 s0, v254, 12
	s_mul_i32 s3, s0, 0x120000
	s_mul_hi_u32 s2, s0, 0x120000
	s_add_u32 s16, s26, s3
	v_readlane_b32 s1, v254, 13
	s_addc_u32 s17, s27, s2
	s_cmp_eq_u32 s0, 0
	v_readlane_b32 s0, v249, 12
	v_readlane_b32 s1, v249, 13
	v_readlane_b32 s4, v249, 16
	v_readlane_b32 s5, v249, 17
	s_cselect_b32 s5, s1, 0
	s_cselect_b32 s4, s0, 0
	s_add_u32 s92, s16, 0x204000
	s_addc_u32 s93, s17, 0
	s_add_u32 s16, s26, 0x19000000
	s_addc_u32 s17, s27, 0
	v_lshl_add_u64 v[0:1], v[0:1], 0, s[64:65]
	s_add_i32 m0, s58, 0x18000
	v_readlane_b32 s2, v249, 14
	v_mov_b32_e32 v243, 0
	s_waitcnt vmcnt(2)
	s_barrier
	global_load_lds_dwordx4 v[0:1], off
	v_lshl_add_u64 v[0:1], v[2:3], 0, s[64:65]
	s_add_i32 m0, s58, 0x1a000
	s_add_i32 s94, s58, 0x8000
	s_add_i32 s95, s58, 0xa000
	v_readlane_b32 s3, v249, 15
	global_load_lds_dwordx4 v[0:1], off
	v_lshl_add_u64 v[0:1], v[4:5], 0, s[64:65]
	s_mov_b32 m0, s94
	s_add_u32 s2, s84, 0x80080
	global_load_lds_dwordx4 v[0:1], off
	v_lshl_add_u64 v[0:1], v[6:7], 0, s[64:65]
	s_mov_b32 m0, s95
	s_addc_u32 s3, s85, 0
	global_load_lds_dwordx4 v[0:1], off
	v_lshl_add_u64 v[0:1], s[2:3], 0, v[96:97]
	s_add_i32 m0, s58, 0x1c000
	v_and_b32_e32 v15, 15, v14
	global_load_lds_dwordx4 v[0:1], off
	v_lshl_add_u64 v[0:1], s[2:3], 0, v[142:143]
	s_add_i32 m0, s58, 0x1e000
	v_readlane_b32 s0, v251, 46
	global_load_lds_dwordx4 v[0:1], off
	v_lshlrev_b32_e32 v0, 15, v11
	v_lshrrev_b32_e32 v16, 1, v14
	v_and_b32_e32 v0, 0xffff0000, v0
	v_or_b32_e32 v168, s0, v15
	v_and_b32_e32 v16, 24, v16
	v_lshl_add_u32 v0, v12, 12, v0
	v_and_b32_e32 v1, 1, v11
	v_lshlrev_b32_e32 v17, 6, v168
	v_lshlrev_b32_e32 v18, 1, v16
	s_movk_i32 s0, 0x3c0
	v_lshlrev_b32_e32 v19, 2, v168
	v_lshl_or_b32 v0, v1, 6, v0
	v_and_or_b32 v17, v17, s0, v18
	v_and_b32_e32 v19, 32, v19
	v_readlane_b32 s0, v251, 47
	v_lshlrev_b32_e32 v14, 2, v14
	v_lshl_add_u32 v148, v13, 1, v0
	v_lshlrev_b32_e32 v0, 15, v8
	v_bitop3_b32 v17, v17, s0, v19 bitop3:0xde
	v_lshl_or_b32 v15, v15, 6, v18
	v_and_b32_e32 v14, 32, v14
	v_readlane_b32 s0, v251, 49
	v_and_b32_e32 v0, 0xffff0000, v0
	s_waitcnt vmcnt(6)
	v_lshl_add_u32 v0, v9, 12, v0
	v_bitop3_b32 v169, v15, s0, v14 bitop3:0xde
	v_readlane_b32 s0, v251, 48
	v_and_b32_e32 v1, 1, v8
	s_cmp_lg_u64 s[4:5], 0
	v_or_b32_e32 v170, s0, v16
	v_lshl_or_b32 v0, v1, 6, v0
	v_readlane_b32 s0, v250, 15
	v_readlane_b32 s54, v253, 60
	s_mov_b32 s91, 0
	s_cselect_b64 s[24:25], -1, 0
	v_mov_b32_e32 v149, v97
	v_lshl_add_u32 v150, v10, 1, v0
	v_mov_b32_e32 v151, v97
	v_add_u32_e32 v171, 0, v17
	v_readlane_b32 s3, v252, 44
	s_mov_b32 s2, s0
	v_readlane_b32 s55, v253, 61
	v_readlane_b32 s6, v249, 18
	v_readlane_b32 s7, v249, 19
	v_readlane_b32 s8, v249, 20
	v_readlane_b32 s9, v249, 21
	v_readlane_b32 s10, v249, 22
	v_readlane_b32 s11, v249, 23
	v_readlane_b32 s12, v249, 24
	v_readlane_b32 s13, v249, 25
	v_readlane_b32 s14, v249, 26
	v_readlane_b32 s15, v249, 27
	s_barrier
	v_readlane_b32 s1, v250, 16
	s_branch .LBB0_1031

.LBB0_1038:
	s_add_u32 s34, s44, 0xfff80080
	s_addc_u32 s35, s45, -1
	s_add_i32 s38, 0, 0x10000
	s_cmp_eq_u32 s33, 28
	s_cselect_b32 s87, s10, s35
	s_cselect_b32 s86, s12, s34
	s_cselect_b32 s85, s18, s31
	s_cselect_b32 s84, s20, s28
	s_add_i32 s39, 0, 0x14000
	v_add_u32_e32 v156, s38, v169
	v_add_u32_e32 v164, s39, v169
	ds_read_b128 v[130:133], v156
	ds_read_b128 v[134:137], v156 offset:1024
	ds_read_b128 v[152:155], v156 offset:2048
	ds_read_b128 v[156:159], v156 offset:3072
	ds_read_b128 v[160:163], v164
	ds_read_b128 v[172:175], v164 offset:1024
	ds_read_b128 v[176:179], v164 offset:2048
	ds_read_b128 v[180:183], v164 offset:3072
	v_lshl_add_u64 v[164:165], s[44:45], 0, v[148:149]
	s_add_i32 m0, s58, 0xc000
	ds_read_b128 v[184:187], v171
	ds_read_b128 v[188:191], v171 offset:1024
	ds_read_b128 v[192:195], v171 offset:2048
	ds_read_b128 v[196:199], v171 offset:3072
	ds_read_b128 v[202:205], v171 offset:4096
	ds_read_b128 v[210:213], v171 offset:5120
	ds_read_b128 v[214:217], v171 offset:6144
	ds_read_b128 v[218:221], v171 offset:7168
	global_load_lds_dwordx4 v[164:165], off
	v_lshl_add_u64 v[164:165], s[44:45], 0, v[150:151]
	s_add_i32 m0, s58, 0xe000
	s_nop 0
	global_load_lds_dwordx4 v[164:165], off
	v_cmp_ne_u32_e32 vcc, 0, v243
	s_cbranch_vccnz .Lrx_G_OUT_0
	s_waitcnt vmcnt(8)
.Lrx_G_OUT_0:
	s_waitcnt vmcnt(44)
	s_waitcnt lgkmcnt(0)
	s_setprio 1
	s_barrier
	v_mfma_f32_16x16x32_bf16 v[126:129], v[130:133], v[184:187], v[126:129]
	v_mfma_f32_16x16x32_bf16 v[122:125], v[152:155], v[184:187], v[122:125]
	v_mfma_f32_16x16x32_bf16 v[110:113], v[130:133], v[192:195], v[110:113]
	v_mfma_f32_16x16x32_bf16 v[106:109], v[152:155], v[192:195], v[106:109]
	v_mfma_f32_16x16x32_bf16 v[92:95], v[130:133], v[202:205], v[92:95]
	v_mfma_f32_16x16x32_bf16 v[88:91], v[152:155], v[202:205], v[88:91]
	v_mfma_f32_16x16x32_bf16 v[76:79], v[130:133], v[214:217], v[76:79]
	v_mfma_f32_16x16x32_bf16 v[72:75], v[152:155], v[214:217], v[72:75]
	v_mfma_f32_16x16x32_bf16 v[126:129], v[134:137], v[188:191], v[126:129]
	v_mfma_f32_16x16x32_bf16 v[122:125], v[156:159], v[188:191], v[122:125]
	v_mfma_f32_16x16x32_bf16 v[110:113], v[134:137], v[196:199], v[110:113]
	v_mfma_f32_16x16x32_bf16 v[106:109], v[156:159], v[196:199], v[106:109]
	v_mfma_f32_16x16x32_bf16 v[92:95], v[134:137], v[210:213], v[92:95]
	v_mfma_f32_16x16x32_bf16 v[88:91], v[156:159], v[210:213], v[88:91]
	v_mfma_f32_16x16x32_bf16 v[76:79], v[134:137], v[218:221], v[76:79]
	v_mfma_f32_16x16x32_bf16 v[72:75], v[156:159], v[218:221], v[72:75]
	v_mfma_f32_16x16x32_bf16 v[118:121], v[160:163], v[184:187], v[118:121]
	v_mfma_f32_16x16x32_bf16 v[114:117], v[176:179], v[184:187], v[114:117]
	v_mfma_f32_16x16x32_bf16 v[102:105], v[160:163], v[192:195], v[102:105]
	v_mfma_f32_16x16x32_bf16 v[98:101], v[176:179], v[192:195], v[98:101]
	v_mfma_f32_16x16x32_bf16 v[84:87], v[160:163], v[202:205], v[84:87]
	v_mfma_f32_16x16x32_bf16 v[80:83], v[176:179], v[202:205], v[80:83]
	v_mfma_f32_16x16x32_bf16 v[68:71], v[160:163], v[214:217], v[68:71]
	v_mfma_f32_16x16x32_bf16 v[64:67], v[176:179], v[214:217], v[64:67]
	v_mfma_f32_16x16x32_bf16 v[118:121], v[172:175], v[188:191], v[118:121]
	v_mfma_f32_16x16x32_bf16 v[114:117], v[180:183], v[188:191], v[114:117]
	v_mfma_f32_16x16x32_bf16 v[102:105], v[172:175], v[196:199], v[102:105]
	v_mfma_f32_16x16x32_bf16 v[98:101], v[180:183], v[196:199], v[98:101]
	v_mfma_f32_16x16x32_bf16 v[84:87], v[172:175], v[210:213], v[84:87]
	v_mfma_f32_16x16x32_bf16 v[80:83], v[180:183], v[210:213], v[80:83]
	v_mfma_f32_16x16x32_bf16 v[68:71], v[172:175], v[218:221], v[68:71]
	v_mfma_f32_16x16x32_bf16 v[64:67], v[180:183], v[218:221], v[64:67]
	s_barrier
	s_setprio 0
	s_add_i32 s34, s38, s75
	v_lshl_add_u64 v[164:165], s[84:85], 0, v[96:97]
	s_mov_b32 m0, s34
	ds_read_b128 v[184:187], v171 offset:16384
	ds_read_b128 v[188:191], v171 offset:17408
	ds_read_b128 v[192:195], v171 offset:18432
	ds_read_b128 v[196:199], v171 offset:19456
	ds_read_b128 v[202:205], v171 offset:20480
	ds_read_b128 v[210:213], v171 offset:21504
	ds_read_b128 v[214:217], v171 offset:22528
	ds_read_b128 v[218:221], v171 offset:23552
	global_load_lds_dwordx4 v[164:165], off
	s_add_i32 m0, s34, 0x2000
	s_add_u32 s34, s84, 0x80000
	v_lshl_add_u64 v[222:223], s[84:85], 0, v[142:143]
	s_addc_u32 s35, s85, 0
	s_add_i32 s38, s39, s75
	global_load_lds_dwordx4 v[222:223], off
	v_lshl_add_u64 v[224:225], s[34:35], 0, v[96:97]
	s_mov_b32 m0, s38
	v_lshl_add_u64 v[226:227], s[86:87], 0, v[144:145]
	global_load_lds_dwordx4 v[224:225], off
	v_lshl_add_u64 v[224:225], s[34:35], 0, v[142:143]
	s_add_i32 m0, s38, 0x2000
	s_nop 0
	global_load_lds_dwordx4 v[224:225], off
	v_lshl_add_u64 v[224:225], s[86:87], 0, v[146:147]
	s_mov_b32 m0, s58
	s_nop 0
	global_load_lds_dwordx4 v[224:225], off
	s_mov_b32 m0, s59
	s_nop 0
	global_load_lds_dwordx4 v[226:227], off
	v_cmp_ne_u32_e32 vcc, 0, v243
	s_cbranch_vccnz .Lrx_G_OUT_1
	s_waitcnt vmcnt(8)
.Lrx_G_OUT_1:
	s_waitcnt vmcnt(44)
	v_mov_b32_e32 v243, 0
	s_waitcnt lgkmcnt(0)
	s_setprio 1
	s_barrier
	v_mfma_f32_16x16x32_bf16 v[60:63], v[130:133], v[184:187], v[60:63]
	v_mfma_f32_16x16x32_bf16 v[56:59], v[152:155], v[184:187], v[56:59]
	v_mfma_f32_16x16x32_bf16 v[44:47], v[130:133], v[192:195], v[44:47]
	v_mfma_f32_16x16x32_bf16 v[40:43], v[152:155], v[192:195], v[40:43]
	v_mfma_f32_16x16x32_bf16 v[28:31], v[130:133], v[202:205], v[28:31]
	v_mfma_f32_16x16x32_bf16 v[24:27], v[152:155], v[202:205], v[24:27]
	v_mfma_f32_16x16x32_bf16 v[12:15], v[130:133], v[214:217], v[12:15]
	v_mfma_f32_16x16x32_bf16 v[8:11], v[152:155], v[214:217], v[8:11]
	v_mfma_f32_16x16x32_bf16 v[60:63], v[134:137], v[188:191], v[60:63]
	v_mfma_f32_16x16x32_bf16 v[56:59], v[156:159], v[188:191], v[56:59]
	v_mfma_f32_16x16x32_bf16 v[44:47], v[134:137], v[196:199], v[44:47]
	v_mfma_f32_16x16x32_bf16 v[40:43], v[156:159], v[196:199], v[40:43]
	v_mfma_f32_16x16x32_bf16 v[28:31], v[134:137], v[210:213], v[28:31]
	v_mfma_f32_16x16x32_bf16 v[24:27], v[156:159], v[210:213], v[24:27]
	v_mfma_f32_16x16x32_bf16 v[12:15], v[134:137], v[218:221], v[12:15]
	v_mfma_f32_16x16x32_bf16 v[8:11], v[156:159], v[218:221], v[8:11]
	v_mfma_f32_16x16x32_bf16 v[52:55], v[160:163], v[184:187], v[52:55]
	v_mfma_f32_16x16x32_bf16 v[48:51], v[176:179], v[184:187], v[48:51]
	v_mfma_f32_16x16x32_bf16 v[36:39], v[160:163], v[192:195], v[36:39]
	v_mfma_f32_16x16x32_bf16 v[32:35], v[176:179], v[192:195], v[32:35]
	v_mfma_f32_16x16x32_bf16 v[20:23], v[160:163], v[202:205], v[20:23]
	v_mfma_f32_16x16x32_bf16 v[16:19], v[176:179], v[202:205], v[16:19]
	v_mfma_f32_16x16x32_bf16 v[4:7], v[160:163], v[214:217], v[4:7]
	v_mfma_f32_16x16x32_bf16 v[0:3], v[176:179], v[214:217], v[0:3]
	v_mfma_f32_16x16x32_bf16 v[52:55], v[172:175], v[188:191], v[52:55]
	v_mfma_f32_16x16x32_bf16 v[48:51], v[180:183], v[188:191], v[48:51]
	v_mfma_f32_16x16x32_bf16 v[36:39], v[172:175], v[196:199], v[36:39]
	v_mfma_f32_16x16x32_bf16 v[32:35], v[180:183], v[196:199], v[32:35]
	v_mfma_f32_16x16x32_bf16 v[20:23], v[172:175], v[210:213], v[20:23]
	v_mfma_f32_16x16x32_bf16 v[16:19], v[180:183], v[210:213], v[16:19]
	v_mfma_f32_16x16x32_bf16 v[4:7], v[172:175], v[218:221], v[4:7]
	v_mfma_f32_16x16x32_bf16 v[0:3], v[180:183], v[218:221], v[0:3]
	s_barrier
	s_setprio 0
	s_add_i32 s38, 0, 0x18000
	s_add_i32 s39, 0, 0x1c000
	v_add_u32_e32 v156, s38, v169
	v_add_u32_e32 v180, s39, v169
	ds_read_b128 v[130:133], v156
	ds_read_b128 v[134:137], v156 offset:1024
	ds_read_b128 v[152:155], v156 offset:2048
	ds_read_b128 v[156:159], v156 offset:3072
	ds_read_b128 v[160:163], v180
	ds_read_b128 v[172:175], v180 offset:1024
	ds_read_b128 v[176:179], v180 offset:2048
	ds_read_b128 v[180:183], v180 offset:3072
	s_add_u32 s34, s86, 0x80000
	s_addc_u32 s35, s87, 0
	s_mov_b32 m0, s79
	v_lshl_add_u64 v[228:229], s[34:35], 0, v[146:147]
	ds_read_b128 v[184:187], v171 offset:32768
	ds_read_b128 v[188:191], v171 offset:33792
	ds_read_b128 v[192:195], v171 offset:34816
	ds_read_b128 v[196:199], v171 offset:35840
	ds_read_b128 v[202:205], v171 offset:36864
	ds_read_b128 v[210:213], v171 offset:37888
	ds_read_b128 v[214:217], v171 offset:38912
	ds_read_b128 v[218:221], v171 offset:39936
	global_load_lds_dwordx4 v[228:229], off
	v_lshl_add_u64 v[228:229], s[34:35], 0, v[144:145]
	s_mov_b32 m0, s90
	s_nop 0
	global_load_lds_dwordx4 v[228:229], off
	s_waitcnt vmcnt(8)
	s_waitcnt lgkmcnt(0)
	s_setprio 1
	s_barrier
	v_mfma_f32_16x16x32_bf16 v[126:129], v[130:133], v[184:187], v[126:129]
	v_mfma_f32_16x16x32_bf16 v[122:125], v[152:155], v[184:187], v[122:125]
	v_mfma_f32_16x16x32_bf16 v[110:113], v[130:133], v[192:195], v[110:113]
	v_mfma_f32_16x16x32_bf16 v[106:109], v[152:155], v[192:195], v[106:109]
	v_mfma_f32_16x16x32_bf16 v[92:95], v[130:133], v[202:205], v[92:95]
	v_mfma_f32_16x16x32_bf16 v[88:91], v[152:155], v[202:205], v[88:91]
	v_mfma_f32_16x16x32_bf16 v[76:79], v[130:133], v[214:217], v[76:79]
	v_mfma_f32_16x16x32_bf16 v[72:75], v[152:155], v[214:217], v[72:75]
	v_mfma_f32_16x16x32_bf16 v[126:129], v[134:137], v[188:191], v[126:129]
	v_mfma_f32_16x16x32_bf16 v[122:125], v[156:159], v[188:191], v[122:125]
	v_mfma_f32_16x16x32_bf16 v[110:113], v[134:137], v[196:199], v[110:113]
	v_mfma_f32_16x16x32_bf16 v[106:109], v[156:159], v[196:199], v[106:109]
	v_mfma_f32_16x16x32_bf16 v[92:95], v[134:137], v[210:213], v[92:95]
	v_mfma_f32_16x16x32_bf16 v[88:91], v[156:159], v[210:213], v[88:91]
	v_mfma_f32_16x16x32_bf16 v[76:79], v[134:137], v[218:221], v[76:79]
	v_mfma_f32_16x16x32_bf16 v[72:75], v[156:159], v[218:221], v[72:75]
	v_mfma_f32_16x16x32_bf16 v[118:121], v[160:163], v[184:187], v[118:121]
	v_mfma_f32_16x16x32_bf16 v[114:117], v[176:179], v[184:187], v[114:117]
	v_mfma_f32_16x16x32_bf16 v[102:105], v[160:163], v[192:195], v[102:105]
	v_mfma_f32_16x16x32_bf16 v[98:101], v[176:179], v[192:195], v[98:101]
	v_mfma_f32_16x16x32_bf16 v[84:87], v[160:163], v[202:205], v[84:87]
	v_mfma_f32_16x16x32_bf16 v[80:83], v[176:179], v[202:205], v[80:83]
	v_mfma_f32_16x16x32_bf16 v[68:71], v[160:163], v[214:217], v[68:71]
	v_mfma_f32_16x16x32_bf16 v[64:67], v[176:179], v[214:217], v[64:67]
	v_mfma_f32_16x16x32_bf16 v[118:121], v[172:175], v[188:191], v[118:121]
	v_mfma_f32_16x16x32_bf16 v[114:117], v[180:183], v[188:191], v[114:117]
	v_mfma_f32_16x16x32_bf16 v[102:105], v[172:175], v[196:199], v[102:105]
	v_mfma_f32_16x16x32_bf16 v[98:101], v[180:183], v[196:199], v[98:101]
	v_mfma_f32_16x16x32_bf16 v[84:87], v[172:175], v[210:213], v[84:87]
	v_mfma_f32_16x16x32_bf16 v[80:83], v[180:183], v[210:213], v[80:83]
	v_mfma_f32_16x16x32_bf16 v[68:71], v[172:175], v[218:221], v[68:71]
	v_mfma_f32_16x16x32_bf16 v[64:67], v[180:183], v[218:221], v[64:67]
	s_barrier
	s_setprio 0
	s_add_i32 s34, s38, s75
	v_lshl_add_u64 v[164:165], v[164:165], 0, s[64:65]
	s_mov_b32 m0, s34
	ds_read_b128 v[184:187], v171 offset:49152
	ds_read_b128 v[188:191], v171 offset:50176
	ds_read_b128 v[192:195], v171 offset:51200
	ds_read_b128 v[196:199], v171 offset:52224
	ds_read_b128 v[202:205], v171 offset:53248
	ds_read_b128 v[210:213], v171 offset:54272
	ds_read_b128 v[214:217], v171 offset:55296
	ds_read_b128 v[218:221], v171 offset:56320
	global_load_lds_dwordx4 v[164:165], off
	s_add_i32 m0, s34, 0x2000
	s_add_u32 s34, s84, 0x80080
	v_lshl_add_u64 v[164:165], v[222:223], 0, s[64:65]
	s_addc_u32 s35, s85, 0
	s_add_i32 s38, s39, s75
	global_load_lds_dwordx4 v[164:165], off
	v_lshl_add_u64 v[164:165], s[34:35], 0, v[96:97]
	s_mov_b32 m0, s38
	s_nop 0
	global_load_lds_dwordx4 v[164:165], off
	v_lshl_add_u64 v[164:165], s[34:35], 0, v[142:143]
	s_add_i32 m0, s38, 0x2000
	s_nop 0
	global_load_lds_dwordx4 v[164:165], off
	v_lshl_add_u64 v[164:165], v[224:225], 0, s[64:65]
	s_mov_b32 m0, s94
	s_nop 0
	global_load_lds_dwordx4 v[164:165], off
	v_lshl_add_u64 v[164:165], v[226:227], 0, s[64:65]
	s_mov_b32 m0, s95
	s_nop 0
	global_load_lds_dwordx4 v[164:165], off
	s_waitcnt vmcnt(8)
	s_waitcnt lgkmcnt(0)
	s_setprio 1
	s_barrier
	v_mfma_f32_16x16x32_bf16 v[60:63], v[130:133], v[184:187], v[60:63]
	v_mfma_f32_16x16x32_bf16 v[56:59], v[152:155], v[184:187], v[56:59]
	v_mfma_f32_16x16x32_bf16 v[44:47], v[130:133], v[192:195], v[44:47]
	v_mfma_f32_16x16x32_bf16 v[40:43], v[152:155], v[192:195], v[40:43]
	v_mfma_f32_16x16x32_bf16 v[28:31], v[130:133], v[202:205], v[28:31]
	v_mfma_f32_16x16x32_bf16 v[24:27], v[152:155], v[202:205], v[24:27]
	v_mfma_f32_16x16x32_bf16 v[12:15], v[130:133], v[214:217], v[12:15]
	v_mfma_f32_16x16x32_bf16 v[8:11], v[152:155], v[214:217], v[8:11]
	v_mfma_f32_16x16x32_bf16 v[60:63], v[134:137], v[188:191], v[60:63]
	v_mfma_f32_16x16x32_bf16 v[56:59], v[156:159], v[188:191], v[56:59]
	v_mfma_f32_16x16x32_bf16 v[44:47], v[134:137], v[196:199], v[44:47]
	v_mfma_f32_16x16x32_bf16 v[40:43], v[156:159], v[196:199], v[40:43]
	v_mfma_f32_16x16x32_bf16 v[28:31], v[134:137], v[210:213], v[28:31]
	v_mfma_f32_16x16x32_bf16 v[24:27], v[156:159], v[210:213], v[24:27]
	v_mfma_f32_16x16x32_bf16 v[12:15], v[134:137], v[218:221], v[12:15]
	v_mfma_f32_16x16x32_bf16 v[8:11], v[156:159], v[218:221], v[8:11]
	v_mfma_f32_16x16x32_bf16 v[52:55], v[160:163], v[184:187], v[52:55]
	v_mfma_f32_16x16x32_bf16 v[48:51], v[176:179], v[184:187], v[48:51]
	v_mfma_f32_16x16x32_bf16 v[36:39], v[160:163], v[192:195], v[36:39]
	v_mfma_f32_16x16x32_bf16 v[32:35], v[176:179], v[192:195], v[32:35]
	v_mfma_f32_16x16x32_bf16 v[20:23], v[160:163], v[202:205], v[20:23]
	v_mfma_f32_16x16x32_bf16 v[16:19], v[176:179], v[202:205], v[16:19]
	v_mfma_f32_16x16x32_bf16 v[4:7], v[160:163], v[214:217], v[4:7]
	v_mfma_f32_16x16x32_bf16 v[0:3], v[176:179], v[214:217], v[0:3]
	v_mfma_f32_16x16x32_bf16 v[52:55], v[172:175], v[188:191], v[52:55]
	v_mfma_f32_16x16x32_bf16 v[48:51], v[180:183], v[188:191], v[48:51]
	v_mfma_f32_16x16x32_bf16 v[36:39], v[172:175], v[196:199], v[36:39]
	v_mfma_f32_16x16x32_bf16 v[32:35], v[180:183], v[196:199], v[32:35]
	v_mfma_f32_16x16x32_bf16 v[20:23], v[172:175], v[210:213], v[20:23]
	v_mfma_f32_16x16x32_bf16 v[16:19], v[180:183], v[210:213], v[16:19]
	v_mfma_f32_16x16x32_bf16 v[4:7], v[172:175], v[218:221], v[4:7]
	v_mfma_f32_16x16x32_bf16 v[0:3], v[180:183], v[218:221], v[0:3]
	s_barrier
	s_setprio 0
	s_add_i32 s33, s33, 2
	s_add_u32 s44, s44, 0x100
	s_addc_u32 s45, s45, 0
	s_add_u32 s28, s28, 0x100
	s_addc_u32 s31, s31, 0
	s_cmp_gt_u32 s33, 29
	s_cbranch_scc0 .LBB0_1038
	v_mov_b32_e32 v243, 1
	v_readlane_b32 s0, v251, 54
	v_readlane_b32 s1, v251, 55
	s_and_b64 vcc, exec, s[0:1]
	s_cbranch_vccz .LBB0_1041
	s_barrier

.LBB0_1255:
	v_readlane_b32 s0, v254, 12
	v_readlane_b32 s1, v254, 13
	s_mov_b32 s2, s0
	s_mul_i32 s1, s2, 0x120000
	s_mul_hi_u32 s0, s0, 0x120000
	s_add_u32 s1, s14, s1
	s_addc_u32 s0, s26, s0
	s_add_u32 s84, s1, 0x20a000
	s_addc_u32 s85, s0, 0
	v_and_b32_e32 v15, 15, v14
	v_readlane_b32 s0, v251, 46
	v_lshrrev_b32_e32 v16, 1, v14
	v_and_b32_e32 v16, 24, v16
	v_or_b32_e32 v152, s0, v15
	v_lshlrev_b32_e32 v17, 6, v152
	v_lshlrev_b32_e32 v18, 1, v16
	s_movk_i32 s0, 0x3c0
	v_lshlrev_b32_e32 v19, 2, v152
	v_and_or_b32 v17, v17, s0, v18
	v_and_b32_e32 v19, 32, v19
	v_readlane_b32 s0, v251, 47
	v_lshlrev_b32_e32 v14, 2, v14
	v_lshl_or_b32 v15, v15, 6, v18
	v_bitop3_b32 v17, v17, s0, v19 bitop3:0xde
	v_and_b32_e32 v14, 32, v14
	v_readlane_b32 s0, v251, 49
	v_lshl_add_u64 v[0:1], v[0:1], 0, s[64:65]
	v_mov_b32_e32 v243, 0
	s_waitcnt vmcnt(2)
	s_barrier
	v_bitop3_b32 v153, v15, s0, v14 bitop3:0xde
	s_add_u32 s0, s14, 0x19000000
	s_addc_u32 s1, s26, 0
	s_add_i32 m0, s59, 0x18000
	s_add_i32 s10, s59, 0x8000
	global_load_lds_dwordx4 v[0:1], off
	v_lshl_add_u64 v[0:1], v[2:3], 0, s[64:65]
	s_add_i32 m0, s59, 0x1a000
	s_add_i32 s77, s59, 0xa000
	global_load_lds_dwordx4 v[0:1], off
	v_lshl_add_u64 v[0:1], v[4:5], 0, s[64:65]
	s_mov_b32 m0, s10
	s_add_u32 s2, s44, 0x200080
	global_load_lds_dwordx4 v[0:1], off
	v_lshl_add_u64 v[0:1], v[6:7], 0, s[64:65]
	s_mov_b32 m0, s77
	s_addc_u32 s3, s45, 0
	global_load_lds_dwordx4 v[0:1], off
	v_lshl_add_u64 v[0:1], s[2:3], 0, v[96:97]
	s_add_i32 m0, s59, 0x1c000
	v_readlane_b32 s4, v250, 15
	global_load_lds_dwordx4 v[0:1], off
	v_lshl_add_u64 v[0:1], s[2:3], 0, v[134:135]
	s_add_i32 m0, s59, 0x1e000
	v_readlane_b32 s2, v251, 48
	global_load_lds_dwordx4 v[0:1], off
	v_lshlrev_b32_e32 v0, 17, v11
	v_and_b32_e32 v0, 0xfffc0000, v0
	v_lshl_add_u32 v0, v12, 14, v0
	v_and_b32_e32 v1, 1, v11
	v_lshl_or_b32 v0, v1, 6, v0
	v_lshl_add_u32 v140, v13, 1, v0
	v_lshlrev_b32_e32 v0, 17, v8
	v_and_b32_e32 v0, 0xfffc0000, v0
	s_waitcnt vmcnt(6)
	v_lshl_add_u32 v0, v9, 14, v0
	v_and_b32_e32 v1, 1, v8
	v_lshl_or_b32 v0, v1, 6, v0
	v_or_b32_e32 v158, s2, v16
	v_mov_b32_e32 v141, v97
	v_lshl_add_u32 v142, v10, 1, v0
	v_mov_b32_e32 v143, v97
	s_mov_b32 s34, 0
	v_add_u32_e32 v159, 0, v17
	v_readlane_b32 s3, v252, 44
	s_mov_b32 s2, s4
	s_barrier
	v_readlane_b32 s5, v250, 16
	s_branch .LBB0_1258

.LBB0_1265:
	s_add_u32 s35, s42, 0xffe00080
	s_addc_u32 s44, s43, -1
	s_add_i32 s54, 0, 0x10000
	s_cmpk_eq_i32 s33, 0x7c
	s_cselect_b32 s53, s12, s44
	s_cselect_b32 s52, s17, s35
	v_add_u32_e32 v148, s54, v153
	s_cselect_b32 s45, s5, s28
	s_cselect_b32 s44, s18, s20
	s_add_i32 s35, 0, 0x14000
	ds_read_b128 v[144:147], v148
	ds_read_b128 v[154:157], v148 offset:1024
	ds_read_b128 v[160:163], v148 offset:2048
	ds_read_b128 v[164:167], v148 offset:3072
	v_add_u32_e32 v148, s35, v153
	ds_read_b128 v[168:171], v148
	ds_read_b128 v[172:175], v148 offset:1024
	ds_read_b128 v[176:179], v148 offset:2048
	ds_read_b128 v[180:183], v148 offset:3072
	v_lshl_add_u64 v[148:149], s[42:43], 0, v[140:141]
	s_add_i32 m0, s59, 0xc000
	ds_read_b128 v[184:187], v159
	ds_read_b128 v[188:191], v159 offset:1024
	ds_read_b128 v[192:195], v159 offset:2048
	ds_read_b128 v[196:199], v159 offset:3072
	ds_read_b128 v[202:205], v159 offset:4096
	ds_read_b128 v[210:213], v159 offset:5120
	ds_read_b128 v[214:217], v159 offset:6144
	ds_read_b128 v[218:221], v159 offset:7168
	global_load_lds_dwordx4 v[148:149], off
	v_lshl_add_u64 v[148:149], s[42:43], 0, v[142:143]
	s_add_i32 m0, s59, 0xe000
	s_nop 0
	global_load_lds_dwordx4 v[148:149], off
	v_cmp_ne_u32_e32 vcc, 0, v243
	s_cbranch_vccnz .Lrx_G_DN_0
	s_waitcnt vmcnt(8)
.Lrx_G_DN_0:
	s_waitcnt vmcnt(44)
	s_waitcnt lgkmcnt(0)
	s_setprio 1
	s_barrier
	v_mfma_f32_16x16x32_bf16 v[126:129], v[144:147], v[184:187], v[126:129]
	v_mfma_f32_16x16x32_bf16 v[122:125], v[160:163], v[184:187], v[122:125]
	v_mfma_f32_16x16x32_bf16 v[110:113], v[144:147], v[192:195], v[110:113]
	v_mfma_f32_16x16x32_bf16 v[106:109], v[160:163], v[192:195], v[106:109]
	v_mfma_f32_16x16x32_bf16 v[92:95], v[144:147], v[202:205], v[92:95]
	v_mfma_f32_16x16x32_bf16 v[88:91], v[160:163], v[202:205], v[88:91]
	v_mfma_f32_16x16x32_bf16 v[76:79], v[144:147], v[214:217], v[76:79]
	v_mfma_f32_16x16x32_bf16 v[72:75], v[160:163], v[214:217], v[72:75]
	v_mfma_f32_16x16x32_bf16 v[126:129], v[154:157], v[188:191], v[126:129]
	v_mfma_f32_16x16x32_bf16 v[122:125], v[164:167], v[188:191], v[122:125]
	v_mfma_f32_16x16x32_bf16 v[110:113], v[154:157], v[196:199], v[110:113]
	v_mfma_f32_16x16x32_bf16 v[106:109], v[164:167], v[196:199], v[106:109]
	v_mfma_f32_16x16x32_bf16 v[92:95], v[154:157], v[210:213], v[92:95]
	v_mfma_f32_16x16x32_bf16 v[88:91], v[164:167], v[210:213], v[88:91]
	v_mfma_f32_16x16x32_bf16 v[76:79], v[154:157], v[218:221], v[76:79]
	v_mfma_f32_16x16x32_bf16 v[72:75], v[164:167], v[218:221], v[72:75]
	v_mfma_f32_16x16x32_bf16 v[118:121], v[168:171], v[184:187], v[118:121]
	v_mfma_f32_16x16x32_bf16 v[114:117], v[176:179], v[184:187], v[114:117]
	v_mfma_f32_16x16x32_bf16 v[102:105], v[168:171], v[192:195], v[102:105]
	v_mfma_f32_16x16x32_bf16 v[98:101], v[176:179], v[192:195], v[98:101]
	v_mfma_f32_16x16x32_bf16 v[84:87], v[168:171], v[202:205], v[84:87]
	v_mfma_f32_16x16x32_bf16 v[80:83], v[176:179], v[202:205], v[80:83]
	v_mfma_f32_16x16x32_bf16 v[68:71], v[168:171], v[214:217], v[68:71]
	v_mfma_f32_16x16x32_bf16 v[64:67], v[176:179], v[214:217], v[64:67]
	v_mfma_f32_16x16x32_bf16 v[118:121], v[172:175], v[188:191], v[118:121]
	v_mfma_f32_16x16x32_bf16 v[114:117], v[180:183], v[188:191], v[114:117]
	v_mfma_f32_16x16x32_bf16 v[102:105], v[172:175], v[196:199], v[102:105]
	v_mfma_f32_16x16x32_bf16 v[98:101], v[180:183], v[196:199], v[98:101]
	v_mfma_f32_16x16x32_bf16 v[84:87], v[172:175], v[210:213], v[84:87]
	v_mfma_f32_16x16x32_bf16 v[80:83], v[180:183], v[210:213], v[80:83]
	v_mfma_f32_16x16x32_bf16 v[68:71], v[172:175], v[218:221], v[68:71]
	v_mfma_f32_16x16x32_bf16 v[64:67], v[180:183], v[218:221], v[64:67]
	s_barrier
	s_setprio 0
	s_add_i32 s54, s54, s75
	v_lshl_add_u64 v[148:149], s[44:45], 0, v[96:97]
	s_mov_b32 m0, s54
	ds_read_b128 v[184:187], v159 offset:16384
	ds_read_b128 v[188:191], v159 offset:17408
	ds_read_b128 v[192:195], v159 offset:18432
	ds_read_b128 v[196:199], v159 offset:19456
	ds_read_b128 v[202:205], v159 offset:20480
	ds_read_b128 v[210:213], v159 offset:21504
	ds_read_b128 v[214:217], v159 offset:22528
	ds_read_b128 v[218:221], v159 offset:23552
	global_load_lds_dwordx4 v[148:149], off
	s_add_i32 m0, s54, 0x2000
	s_add_u32 s54, s44, 0x200000
	v_lshl_add_u64 v[222:223], s[44:45], 0, v[134:135]
	s_addc_u32 s55, s45, 0
	s_add_i32 s35, s35, s75
	global_load_lds_dwordx4 v[222:223], off
	v_lshl_add_u64 v[224:225], s[54:55], 0, v[96:97]
	s_mov_b32 m0, s35
	v_lshl_add_u64 v[226:227], s[52:53], 0, v[136:137]
	global_load_lds_dwordx4 v[224:225], off
	v_lshl_add_u64 v[224:225], s[54:55], 0, v[134:135]
	s_add_i32 m0, s35, 0x2000
	s_nop 0
	global_load_lds_dwordx4 v[224:225], off
	v_lshl_add_u64 v[224:225], s[52:53], 0, v[138:139]
	s_mov_b32 m0, s59
	s_nop 0
	global_load_lds_dwordx4 v[224:225], off
	s_mov_b32 m0, s68
	s_nop 0
	global_load_lds_dwordx4 v[226:227], off
	v_cmp_ne_u32_e32 vcc, 0, v243
	s_cbranch_vccnz .Lrx_G_DN_1
	s_waitcnt vmcnt(8)
.Lrx_G_DN_1:
	s_waitcnt vmcnt(44)
	v_mov_b32_e32 v243, 0
	s_waitcnt lgkmcnt(0)
	s_setprio 1
	s_barrier
	v_mfma_f32_16x16x32_bf16 v[60:63], v[144:147], v[184:187], v[60:63]
	v_mfma_f32_16x16x32_bf16 v[56:59], v[160:163], v[184:187], v[56:59]
	v_mfma_f32_16x16x32_bf16 v[44:47], v[144:147], v[192:195], v[44:47]
	v_mfma_f32_16x16x32_bf16 v[40:43], v[160:163], v[192:195], v[40:43]
	v_mfma_f32_16x16x32_bf16 v[28:31], v[144:147], v[202:205], v[28:31]
	v_mfma_f32_16x16x32_bf16 v[24:27], v[160:163], v[202:205], v[24:27]
	v_mfma_f32_16x16x32_bf16 v[12:15], v[144:147], v[214:217], v[12:15]
	v_mfma_f32_16x16x32_bf16 v[8:11], v[160:163], v[214:217], v[8:11]
	v_mfma_f32_16x16x32_bf16 v[60:63], v[154:157], v[188:191], v[60:63]
	v_mfma_f32_16x16x32_bf16 v[56:59], v[164:167], v[188:191], v[56:59]
	v_mfma_f32_16x16x32_bf16 v[44:47], v[154:157], v[196:199], v[44:47]
	v_mfma_f32_16x16x32_bf16 v[40:43], v[164:167], v[196:199], v[40:43]
	v_mfma_f32_16x16x32_bf16 v[28:31], v[154:157], v[210:213], v[28:31]
	v_mfma_f32_16x16x32_bf16 v[24:27], v[164:167], v[210:213], v[24:27]
	v_mfma_f32_16x16x32_bf16 v[12:15], v[154:157], v[218:221], v[12:15]
	v_mfma_f32_16x16x32_bf16 v[8:11], v[164:167], v[218:221], v[8:11]
	v_mfma_f32_16x16x32_bf16 v[52:55], v[168:171], v[184:187], v[52:55]
	v_mfma_f32_16x16x32_bf16 v[48:51], v[176:179], v[184:187], v[48:51]
	v_mfma_f32_16x16x32_bf16 v[36:39], v[168:171], v[192:195], v[36:39]
	v_mfma_f32_16x16x32_bf16 v[32:35], v[176:179], v[192:195], v[32:35]
	v_mfma_f32_16x16x32_bf16 v[20:23], v[168:171], v[202:205], v[20:23]
	v_mfma_f32_16x16x32_bf16 v[16:19], v[176:179], v[202:205], v[16:19]
	v_mfma_f32_16x16x32_bf16 v[4:7], v[168:171], v[214:217], v[4:7]
	v_mfma_f32_16x16x32_bf16 v[0:3], v[176:179], v[214:217], v[0:3]
	v_mfma_f32_16x16x32_bf16 v[52:55], v[172:175], v[188:191], v[52:55]
	v_mfma_f32_16x16x32_bf16 v[48:51], v[180:183], v[188:191], v[48:51]
	v_mfma_f32_16x16x32_bf16 v[36:39], v[172:175], v[196:199], v[36:39]
	v_mfma_f32_16x16x32_bf16 v[32:35], v[180:183], v[196:199], v[32:35]
	v_mfma_f32_16x16x32_bf16 v[20:23], v[172:175], v[210:213], v[20:23]
	v_mfma_f32_16x16x32_bf16 v[16:19], v[180:183], v[210:213], v[16:19]
	v_mfma_f32_16x16x32_bf16 v[4:7], v[172:175], v[218:221], v[4:7]
	v_mfma_f32_16x16x32_bf16 v[0:3], v[180:183], v[218:221], v[0:3]
	s_barrier
	s_setprio 0
	s_add_i32 s35, 0, 0x18000
	s_add_i32 s54, 0, 0x1c000
	v_add_u32_e32 v164, s35, v153
	v_add_u32_e32 v180, s54, v153
	ds_read_b128 v[144:147], v164
	ds_read_b128 v[154:157], v164 offset:1024
	ds_read_b128 v[160:163], v164 offset:2048
	ds_read_b128 v[164:167], v164 offset:3072
	ds_read_b128 v[168:171], v180
	ds_read_b128 v[172:175], v180 offset:1024
	ds_read_b128 v[176:179], v180 offset:2048
	ds_read_b128 v[180:183], v180 offset:3072
	s_add_u32 s52, s52, 0x200000
	s_addc_u32 s53, s53, 0
	s_mov_b32 m0, s69
	v_lshl_add_u64 v[228:229], s[52:53], 0, v[138:139]
	ds_read_b128 v[184:187], v159 offset:32768
	ds_read_b128 v[188:191], v159 offset:33792
	ds_read_b128 v[192:195], v159 offset:34816
	ds_read_b128 v[196:199], v159 offset:35840
	ds_read_b128 v[202:205], v159 offset:36864
	ds_read_b128 v[210:213], v159 offset:37888
	ds_read_b128 v[214:217], v159 offset:38912
	ds_read_b128 v[218:221], v159 offset:39936
	global_load_lds_dwordx4 v[228:229], off
	v_lshl_add_u64 v[228:229], s[52:53], 0, v[136:137]
	s_mov_b32 m0, s79
	s_nop 0
	global_load_lds_dwordx4 v[228:229], off
	s_waitcnt vmcnt(8)
	s_waitcnt lgkmcnt(0)
	s_setprio 1
	s_barrier
	v_mfma_f32_16x16x32_bf16 v[126:129], v[144:147], v[184:187], v[126:129]
	v_mfma_f32_16x16x32_bf16 v[122:125], v[160:163], v[184:187], v[122:125]
	v_mfma_f32_16x16x32_bf16 v[110:113], v[144:147], v[192:195], v[110:113]
	v_mfma_f32_16x16x32_bf16 v[106:109], v[160:163], v[192:195], v[106:109]
	v_mfma_f32_16x16x32_bf16 v[92:95], v[144:147], v[202:205], v[92:95]
	v_mfma_f32_16x16x32_bf16 v[88:91], v[160:163], v[202:205], v[88:91]
	v_mfma_f32_16x16x32_bf16 v[76:79], v[144:147], v[214:217], v[76:79]
	v_mfma_f32_16x16x32_bf16 v[72:75], v[160:163], v[214:217], v[72:75]
	v_mfma_f32_16x16x32_bf16 v[126:129], v[154:157], v[188:191], v[126:129]
	v_mfma_f32_16x16x32_bf16 v[122:125], v[164:167], v[188:191], v[122:125]
	v_mfma_f32_16x16x32_bf16 v[110:113], v[154:157], v[196:199], v[110:113]
	v_mfma_f32_16x16x32_bf16 v[106:109], v[164:167], v[196:199], v[106:109]
	v_mfma_f32_16x16x32_bf16 v[92:95], v[154:157], v[210:213], v[92:95]
	v_mfma_f32_16x16x32_bf16 v[88:91], v[164:167], v[210:213], v[88:91]
	v_mfma_f32_16x16x32_bf16 v[76:79], v[154:157], v[218:221], v[76:79]
	v_mfma_f32_16x16x32_bf16 v[72:75], v[164:167], v[218:221], v[72:75]
	v_mfma_f32_16x16x32_bf16 v[118:121], v[168:171], v[184:187], v[118:121]
	v_mfma_f32_16x16x32_bf16 v[114:117], v[176:179], v[184:187], v[114:117]
	v_mfma_f32_16x16x32_bf16 v[102:105], v[168:171], v[192:195], v[102:105]
	v_mfma_f32_16x16x32_bf16 v[98:101], v[176:179], v[192:195], v[98:101]
	v_mfma_f32_16x16x32_bf16 v[84:87], v[168:171], v[202:205], v[84:87]
	v_mfma_f32_16x16x32_bf16 v[80:83], v[176:179], v[202:205], v[80:83]
	v_mfma_f32_16x16x32_bf16 v[68:71], v[168:171], v[214:217], v[68:71]
	v_mfma_f32_16x16x32_bf16 v[64:67], v[176:179], v[214:217], v[64:67]
	v_mfma_f32_16x16x32_bf16 v[118:121], v[172:175], v[188:191], v[118:121]
	v_mfma_f32_16x16x32_bf16 v[114:117], v[180:183], v[188:191], v[114:117]
	v_mfma_f32_16x16x32_bf16 v[102:105], v[172:175], v[196:199], v[102:105]
	v_mfma_f32_16x16x32_bf16 v[98:101], v[180:183], v[196:199], v[98:101]
	v_mfma_f32_16x16x32_bf16 v[84:87], v[172:175], v[210:213], v[84:87]
	v_mfma_f32_16x16x32_bf16 v[80:83], v[180:183], v[210:213], v[80:83]
	v_mfma_f32_16x16x32_bf16 v[68:71], v[172:175], v[218:221], v[68:71]
	v_mfma_f32_16x16x32_bf16 v[64:67], v[180:183], v[218:221], v[64:67]
	s_barrier
	s_setprio 0
	s_add_i32 s35, s35, s75
	v_lshl_add_u64 v[148:149], v[148:149], 0, s[64:65]
	s_mov_b32 m0, s35
	ds_read_b128 v[184:187], v159 offset:49152
	ds_read_b128 v[188:191], v159 offset:50176
	ds_read_b128 v[192:195], v159 offset:51200
	ds_read_b128 v[196:199], v159 offset:52224
	ds_read_b128 v[202:205], v159 offset:53248
	ds_read_b128 v[210:213], v159 offset:54272
	ds_read_b128 v[214:217], v159 offset:55296
	ds_read_b128 v[218:221], v159 offset:56320
	global_load_lds_dwordx4 v[148:149], off
	s_add_i32 m0, s35, 0x2000
	s_add_u32 s44, s44, 0x200080
	v_lshl_add_u64 v[148:149], v[222:223], 0, s[64:65]
	s_addc_u32 s45, s45, 0
	s_add_i32 s35, s54, s75
	global_load_lds_dwordx4 v[148:149], off
	v_lshl_add_u64 v[148:149], s[44:45], 0, v[96:97]
	s_mov_b32 m0, s35
	s_nop 0
	global_load_lds_dwordx4 v[148:149], off
	v_lshl_add_u64 v[148:149], s[44:45], 0, v[134:135]
	s_add_i32 m0, s35, 0x2000
	s_nop 0
	global_load_lds_dwordx4 v[148:149], off
	v_lshl_add_u64 v[148:149], v[224:225], 0, s[64:65]
	s_mov_b32 m0, s10
	s_nop 0
	global_load_lds_dwordx4 v[148:149], off
	v_lshl_add_u64 v[148:149], v[226:227], 0, s[64:65]
	s_mov_b32 m0, s77
	s_nop 0
	global_load_lds_dwordx4 v[148:149], off
	s_waitcnt vmcnt(8)
	s_waitcnt lgkmcnt(0)
	s_setprio 1
	s_barrier
	v_mfma_f32_16x16x32_bf16 v[60:63], v[144:147], v[184:187], v[60:63]
	v_mfma_f32_16x16x32_bf16 v[56:59], v[160:163], v[184:187], v[56:59]
	v_mfma_f32_16x16x32_bf16 v[44:47], v[144:147], v[192:195], v[44:47]
	v_mfma_f32_16x16x32_bf16 v[40:43], v[160:163], v[192:195], v[40:43]
	v_mfma_f32_16x16x32_bf16 v[28:31], v[144:147], v[202:205], v[28:31]
	v_mfma_f32_16x16x32_bf16 v[24:27], v[160:163], v[202:205], v[24:27]
	v_mfma_f32_16x16x32_bf16 v[12:15], v[144:147], v[214:217], v[12:15]
	v_mfma_f32_16x16x32_bf16 v[8:11], v[160:163], v[214:217], v[8:11]
	v_mfma_f32_16x16x32_bf16 v[60:63], v[154:157], v[188:191], v[60:63]
	v_mfma_f32_16x16x32_bf16 v[56:59], v[164:167], v[188:191], v[56:59]
	v_mfma_f32_16x16x32_bf16 v[44:47], v[154:157], v[196:199], v[44:47]
	v_mfma_f32_16x16x32_bf16 v[40:43], v[164:167], v[196:199], v[40:43]
	v_mfma_f32_16x16x32_bf16 v[28:31], v[154:157], v[210:213], v[28:31]
	v_mfma_f32_16x16x32_bf16 v[24:27], v[164:167], v[210:213], v[24:27]
	v_mfma_f32_16x16x32_bf16 v[12:15], v[154:157], v[218:221], v[12:15]
	v_mfma_f32_16x16x32_bf16 v[8:11], v[164:167], v[218:221], v[8:11]
	v_mfma_f32_16x16x32_bf16 v[52:55], v[168:171], v[184:187], v[52:55]
	v_mfma_f32_16x16x32_bf16 v[48:51], v[176:179], v[184:187], v[48:51]
	v_mfma_f32_16x16x32_bf16 v[36:39], v[168:171], v[192:195], v[36:39]
	v_mfma_f32_16x16x32_bf16 v[32:35], v[176:179], v[192:195], v[32:35]
	v_mfma_f32_16x16x32_bf16 v[20:23], v[168:171], v[202:205], v[20:23]
	v_mfma_f32_16x16x32_bf16 v[16:19], v[176:179], v[202:205], v[16:19]
	v_mfma_f32_16x16x32_bf16 v[4:7], v[168:171], v[214:217], v[4:7]
	v_mfma_f32_16x16x32_bf16 v[0:3], v[176:179], v[214:217], v[0:3]
	v_mfma_f32_16x16x32_bf16 v[52:55], v[172:175], v[188:191], v[52:55]
	v_mfma_f32_16x16x32_bf16 v[48:51], v[180:183], v[188:191], v[48:51]
	v_mfma_f32_16x16x32_bf16 v[36:39], v[172:175], v[196:199], v[36:39]
	v_mfma_f32_16x16x32_bf16 v[32:35], v[180:183], v[196:199], v[32:35]
	v_mfma_f32_16x16x32_bf16 v[20:23], v[172:175], v[210:213], v[20:23]
	v_mfma_f32_16x16x32_bf16 v[16:19], v[180:183], v[210:213], v[16:19]
	v_mfma_f32_16x16x32_bf16 v[4:7], v[172:175], v[218:221], v[4:7]
	v_mfma_f32_16x16x32_bf16 v[0:3], v[180:183], v[218:221], v[0:3]
	s_barrier
	s_setprio 0
	s_add_i32 s33, s33, 2
	s_add_u32 s42, s42, 0x100
	s_addc_u32 s43, s43, 0
	s_add_u32 s20, s20, 0x100
	s_addc_u32 s28, s28, 0
	s_cmpk_gt_u32 s33, 0x7d
	s_cbranch_scc0 .LBB0_1265
	v_mov_b32_e32 v243, 1
	v_readlane_b32 s6, v251, 54
	v_readlane_b32 s7, v251, 55
	s_and_b64 vcc, exec, s[6:7]
	s_movk_i32 s53, 0x6000
	s_cbranch_vccz .LBB0_1268
	s_barrier

.LBB0_1274:
	v_and_b32_e32 v7, 15, v6
	v_readlane_b32 s0, v251, 46
	v_lshrrev_b32_e32 v16, 1, v6
	v_and_b32_e32 v16, 24, v16
	v_or_b32_e32 v133, s0, v7
	v_lshlrev_b32_e32 v17, 6, v133
	v_lshlrev_b32_e32 v18, 1, v16
	s_movk_i32 s0, 0x3c0
	v_lshlrev_b32_e32 v19, 2, v133
	v_and_or_b32 v17, v17, s0, v18
	v_and_b32_e32 v19, 32, v19
	v_readlane_b32 s0, v251, 47
	v_lshlrev_b32_e32 v6, 2, v6
	v_lshl_or_b32 v7, v7, 6, v18
	v_bitop3_b32 v17, v17, s0, v19 bitop3:0xde
	v_and_b32_e32 v6, 32, v6
	v_readlane_b32 s0, v251, 49
	v_lshl_add_u64 v[8:9], s[68:69], 0, v[96:97]
	v_mov_b32_e32 v135, v97
	v_bitop3_b32 v150, v7, s0, v6 bitop3:0xde
	v_readlane_b32 s0, v254, 30
	v_readlane_b32 s1, v254, 31
	s_add_u32 s4, s0, 0x25400000
	v_lshl_add_u64 v[10:11], s[68:69], 0, v[134:135]
	v_mov_b32_e32 v139, v97
	s_addc_u32 s5, s1, 0
	v_lshl_add_u64 v[6:7], v[8:9], 0, s[64:65]
	s_add_i32 m0, s34, 0x18000
	v_lshl_add_u64 v[12:13], s[52:53], 0, v[138:139]
	v_mov_b32_e32 v137, v97
	v_mov_b32_e32 v243, 0
	s_waitcnt vmcnt(2)
	s_barrier
	global_load_lds_dwordx4 v[6:7], off
	v_lshl_add_u64 v[6:7], v[10:11], 0, s[64:65]
	s_add_i32 m0, s34, 0x1a000
	s_add_i32 s58, s34, 0x8000
	s_add_i32 s59, s34, 0xa000
	v_lshl_add_u64 v[14:15], s[52:53], 0, v[136:137]
	global_load_lds_dwordx4 v[6:7], off
	v_lshl_add_u64 v[6:7], v[12:13], 0, s[64:65]
	s_mov_b32 m0, s58
	s_add_u32 s0, s68, 0x80080
	global_load_lds_dwordx4 v[6:7], off
	v_lshl_add_u64 v[6:7], v[14:15], 0, s[64:65]
	s_mov_b32 m0, s59
	s_addc_u32 s1, s69, 0
	global_load_lds_dwordx4 v[6:7], off
	v_lshl_add_u64 v[6:7], s[0:1], 0, v[96:97]
	s_add_i32 m0, s34, 0x1c000
	v_mov_b32_e32 v141, v97
	global_load_lds_dwordx4 v[6:7], off
	v_lshl_add_u64 v[6:7], s[0:1], 0, v[134:135]
	s_add_i32 m0, s34, 0x1e000
	v_readlane_b32 s0, v251, 48
	global_load_lds_dwordx4 v[6:7], off
	v_lshlrev_b32_e32 v6, 15, v3
	v_and_b32_e32 v6, 0xffff0000, v6
	v_lshl_add_u32 v4, v4, 12, v6
	v_and_b32_e32 v3, 1, v3
	v_lshl_or_b32 v3, v3, 6, v4
	v_lshl_add_u32 v140, v5, 1, v3
	v_lshlrev_b32_e32 v3, 15, v0
	v_and_b32_e32 v3, 0xffff0000, v3
	s_waitcnt vmcnt(6)
	v_lshl_add_u32 v1, v1, 12, v3
	v_and_b32_e32 v0, 1, v0
	v_lshl_or_b32 v0, v0, 6, v1
	v_or_b32_e32 v151, s0, v16
	v_lshl_add_u32 v142, v2, 1, v0
	v_mov_b32_e32 v143, v97
	s_mov_b32 s0, 0
	v_add_u32_e32 v152, 0, v17
	v_readlane_b32 s1, v252, 51
	v_readlane_b32 s2, v250, 5
	s_barrier
	v_readlane_b32 s3, v250, 6
	s_branch .LBB0_1277

.LBB0_1284:
	s_add_u32 s33, s52, 0xfff80080
	s_addc_u32 s38, s53, -1
	s_add_i32 s39, 0, 0x10000
	s_cmp_eq_u32 s28, 28
	s_cselect_b32 s83, s3, s38
	s_cselect_b32 s82, s12, s33
	v_add_u32_e32 v144, s39, v150
	s_cselect_b32 s69, s17, s25
	s_cselect_b32 s68, s18, s20
	s_add_i32 s33, 0, 0x14000
	ds_read_b128 v[154:157], v144
	ds_read_b128 v[158:161], v144 offset:1024
	ds_read_b128 v[162:165], v144 offset:2048
	ds_read_b128 v[166:169], v144 offset:3072
	v_add_u32_e32 v144, s33, v150
	ds_read_b128 v[170:173], v144
	ds_read_b128 v[174:177], v144 offset:1024
	ds_read_b128 v[178:181], v144 offset:2048
	ds_read_b128 v[182:185], v144 offset:3072
	v_lshl_add_u64 v[144:145], s[52:53], 0, v[140:141]
	s_add_i32 m0, s34, 0xc000
	ds_read_b128 v[186:189], v152
	ds_read_b128 v[190:193], v152 offset:1024
	ds_read_b128 v[194:197], v152 offset:2048
	ds_read_b128 v[202:205], v152 offset:3072
	ds_read_b128 v[210:213], v152 offset:4096
	ds_read_b128 v[214:217], v152 offset:5120
	ds_read_b128 v[218:221], v152 offset:6144
	ds_read_b128 v[222:225], v152 offset:7168
	global_load_lds_dwordx4 v[144:145], off
	v_lshl_add_u64 v[144:145], s[52:53], 0, v[142:143]
	s_add_i32 m0, s34, 0xe000
	s_nop 0
	global_load_lds_dwordx4 v[144:145], off
	v_cmp_ne_u32_e32 vcc, 0, v243
	s_cbranch_vccnz .Lrx_G_UP_0
	s_waitcnt vmcnt(8)
.Lrx_G_UP_0:
	s_waitcnt vmcnt(24)
	s_waitcnt lgkmcnt(0)
	s_setprio 1
	s_barrier
	v_mfma_f32_16x16x32_bf16 v[126:129], v[154:157], v[186:189], v[126:129]
	v_mfma_f32_16x16x32_bf16 v[122:125], v[162:165], v[186:189], v[122:125]
	v_mfma_f32_16x16x32_bf16 v[110:113], v[154:157], v[194:197], v[110:113]
	v_mfma_f32_16x16x32_bf16 v[106:109], v[162:165], v[194:197], v[106:109]
	v_mfma_f32_16x16x32_bf16 v[92:95], v[154:157], v[210:213], v[92:95]
	v_mfma_f32_16x16x32_bf16 v[88:91], v[162:165], v[210:213], v[88:91]
	v_mfma_f32_16x16x32_bf16 v[76:79], v[154:157], v[218:221], v[76:79]
	v_mfma_f32_16x16x32_bf16 v[72:75], v[162:165], v[218:221], v[72:75]
	v_mfma_f32_16x16x32_bf16 v[126:129], v[158:161], v[190:193], v[126:129]
	v_mfma_f32_16x16x32_bf16 v[122:125], v[166:169], v[190:193], v[122:125]
	v_mfma_f32_16x16x32_bf16 v[110:113], v[158:161], v[202:205], v[110:113]
	v_mfma_f32_16x16x32_bf16 v[106:109], v[166:169], v[202:205], v[106:109]
	v_mfma_f32_16x16x32_bf16 v[92:95], v[158:161], v[214:217], v[92:95]
	v_mfma_f32_16x16x32_bf16 v[88:91], v[166:169], v[214:217], v[88:91]
	v_mfma_f32_16x16x32_bf16 v[76:79], v[158:161], v[222:225], v[76:79]
	v_mfma_f32_16x16x32_bf16 v[72:75], v[166:169], v[222:225], v[72:75]
	v_mfma_f32_16x16x32_bf16 v[118:121], v[170:173], v[186:189], v[118:121]
	v_mfma_f32_16x16x32_bf16 v[114:117], v[178:181], v[186:189], v[114:117]
	v_mfma_f32_16x16x32_bf16 v[102:105], v[170:173], v[194:197], v[102:105]
	v_mfma_f32_16x16x32_bf16 v[98:101], v[178:181], v[194:197], v[98:101]
	v_mfma_f32_16x16x32_bf16 v[84:87], v[170:173], v[210:213], v[84:87]
	v_mfma_f32_16x16x32_bf16 v[80:83], v[178:181], v[210:213], v[80:83]
	v_mfma_f32_16x16x32_bf16 v[68:71], v[170:173], v[218:221], v[68:71]
	v_mfma_f32_16x16x32_bf16 v[64:67], v[178:181], v[218:221], v[64:67]
	v_mfma_f32_16x16x32_bf16 v[118:121], v[174:177], v[190:193], v[118:121]
	v_mfma_f32_16x16x32_bf16 v[114:117], v[182:185], v[190:193], v[114:117]
	v_mfma_f32_16x16x32_bf16 v[102:105], v[174:177], v[202:205], v[102:105]
	v_mfma_f32_16x16x32_bf16 v[98:101], v[182:185], v[202:205], v[98:101]
	v_mfma_f32_16x16x32_bf16 v[84:87], v[174:177], v[214:217], v[84:87]
	v_mfma_f32_16x16x32_bf16 v[80:83], v[182:185], v[214:217], v[80:83]
	v_mfma_f32_16x16x32_bf16 v[68:71], v[174:177], v[222:225], v[68:71]
	v_mfma_f32_16x16x32_bf16 v[64:67], v[182:185], v[222:225], v[64:67]
	s_barrier
	s_setprio 0
	s_add_i32 s38, s39, s75
	v_lshl_add_u64 v[144:145], s[68:69], 0, v[96:97]
	s_mov_b32 m0, s38
	ds_read_b128 v[186:189], v152 offset:16384
	ds_read_b128 v[190:193], v152 offset:17408
	ds_read_b128 v[194:197], v152 offset:18432
	ds_read_b128 v[202:205], v152 offset:19456
	ds_read_b128 v[210:213], v152 offset:20480
	ds_read_b128 v[214:217], v152 offset:21504
	ds_read_b128 v[218:221], v152 offset:22528
	ds_read_b128 v[222:225], v152 offset:23552
	global_load_lds_dwordx4 v[144:145], off
	s_add_i32 m0, s38, 0x2000
	s_add_u32 s38, s68, 0x80000
	v_lshl_add_u64 v[198:199], s[68:69], 0, v[134:135]
	s_addc_u32 s39, s69, 0
	s_add_i32 s33, s33, s75
	global_load_lds_dwordx4 v[198:199], off
	v_lshl_add_u64 v[226:227], s[38:39], 0, v[96:97]
	s_mov_b32 m0, s33
	v_lshl_add_u64 v[228:229], s[82:83], 0, v[136:137]
	global_load_lds_dwordx4 v[226:227], off
	v_lshl_add_u64 v[226:227], s[38:39], 0, v[134:135]
	s_add_i32 m0, s33, 0x2000
	s_nop 0
	global_load_lds_dwordx4 v[226:227], off
	v_lshl_add_u64 v[226:227], s[82:83], 0, v[138:139]
	s_mov_b32 m0, s34
	s_nop 0
	global_load_lds_dwordx4 v[226:227], off
	s_mov_b32 m0, s35
	s_nop 0
	global_load_lds_dwordx4 v[228:229], off
	v_cmp_ne_u32_e32 vcc, 0, v243
	s_cbranch_vccnz .Lrx_G_UP_1
	s_waitcnt vmcnt(8)
.Lrx_G_UP_1:
	s_waitcnt vmcnt(24)
	v_mov_b32_e32 v243, 0
	s_waitcnt lgkmcnt(0)
	s_setprio 1
	s_barrier
	v_mfma_f32_16x16x32_bf16 v[60:63], v[154:157], v[186:189], v[60:63]
	v_mfma_f32_16x16x32_bf16 v[56:59], v[162:165], v[186:189], v[56:59]
	v_mfma_f32_16x16x32_bf16 v[44:47], v[154:157], v[194:197], v[44:47]
	v_mfma_f32_16x16x32_bf16 v[40:43], v[162:165], v[194:197], v[40:43]
	v_mfma_f32_16x16x32_bf16 v[28:31], v[154:157], v[210:213], v[28:31]
	v_mfma_f32_16x16x32_bf16 v[24:27], v[162:165], v[210:213], v[24:27]
	v_mfma_f32_16x16x32_bf16 v[12:15], v[154:157], v[218:221], v[12:15]
	v_mfma_f32_16x16x32_bf16 v[8:11], v[162:165], v[218:221], v[8:11]
	v_mfma_f32_16x16x32_bf16 v[60:63], v[158:161], v[190:193], v[60:63]
	v_mfma_f32_16x16x32_bf16 v[56:59], v[166:169], v[190:193], v[56:59]
	v_mfma_f32_16x16x32_bf16 v[44:47], v[158:161], v[202:205], v[44:47]
	v_mfma_f32_16x16x32_bf16 v[40:43], v[166:169], v[202:205], v[40:43]
	v_mfma_f32_16x16x32_bf16 v[28:31], v[158:161], v[214:217], v[28:31]
	v_mfma_f32_16x16x32_bf16 v[24:27], v[166:169], v[214:217], v[24:27]
	v_mfma_f32_16x16x32_bf16 v[12:15], v[158:161], v[222:225], v[12:15]
	v_mfma_f32_16x16x32_bf16 v[8:11], v[166:169], v[222:225], v[8:11]
	v_mfma_f32_16x16x32_bf16 v[52:55], v[170:173], v[186:189], v[52:55]
	v_mfma_f32_16x16x32_bf16 v[48:51], v[178:181], v[186:189], v[48:51]
	v_mfma_f32_16x16x32_bf16 v[36:39], v[170:173], v[194:197], v[36:39]
	v_mfma_f32_16x16x32_bf16 v[32:35], v[178:181], v[194:197], v[32:35]
	v_mfma_f32_16x16x32_bf16 v[20:23], v[170:173], v[210:213], v[20:23]
	v_mfma_f32_16x16x32_bf16 v[16:19], v[178:181], v[210:213], v[16:19]
	v_mfma_f32_16x16x32_bf16 v[4:7], v[170:173], v[218:221], v[4:7]
	v_mfma_f32_16x16x32_bf16 v[0:3], v[178:181], v[218:221], v[0:3]
	v_mfma_f32_16x16x32_bf16 v[52:55], v[174:177], v[190:193], v[52:55]
	v_mfma_f32_16x16x32_bf16 v[48:51], v[182:185], v[190:193], v[48:51]
	v_mfma_f32_16x16x32_bf16 v[36:39], v[174:177], v[202:205], v[36:39]
	v_mfma_f32_16x16x32_bf16 v[32:35], v[182:185], v[202:205], v[32:35]
	v_mfma_f32_16x16x32_bf16 v[20:23], v[174:177], v[214:217], v[20:23]
	v_mfma_f32_16x16x32_bf16 v[16:19], v[182:185], v[214:217], v[16:19]
	v_mfma_f32_16x16x32_bf16 v[4:7], v[174:177], v[222:225], v[4:7]
	v_mfma_f32_16x16x32_bf16 v[0:3], v[182:185], v[222:225], v[0:3]
	s_barrier
	s_setprio 0
	s_add_i32 s33, 0, 0x18000
	v_add_u32_e32 v153, s33, v150
	s_add_i32 s54, 0, 0x1c000
	ds_read_b128 v[154:157], v153
	ds_read_b128 v[158:161], v153 offset:1024
	ds_read_b128 v[162:165], v153 offset:2048
	ds_read_b128 v[166:169], v153 offset:3072
	v_add_u32_e32 v153, s54, v150
	ds_read_b128 v[170:173], v153
	ds_read_b128 v[174:177], v153 offset:1024
	ds_read_b128 v[178:181], v153 offset:2048
	ds_read_b128 v[182:185], v153 offset:3072
	s_add_u32 s38, s82, 0x80000
	s_addc_u32 s39, s83, 0
	s_mov_b32 m0, s50
	v_lshl_add_u64 v[230:231], s[38:39], 0, v[138:139]
	ds_read_b128 v[186:189], v152 offset:32768
	ds_read_b128 v[190:193], v152 offset:33792
	ds_read_b128 v[194:197], v152 offset:34816
	ds_read_b128 v[202:205], v152 offset:35840
	ds_read_b128 v[210:213], v152 offset:36864
	ds_read_b128 v[214:217], v152 offset:37888
	ds_read_b128 v[218:221], v152 offset:38912
	ds_read_b128 v[222:225], v152 offset:39936
	global_load_lds_dwordx4 v[230:231], off
	v_lshl_add_u64 v[230:231], s[38:39], 0, v[136:137]
	s_mov_b32 m0, s51
	s_nop 0
	global_load_lds_dwordx4 v[230:231], off
	s_waitcnt vmcnt(8)
	s_waitcnt lgkmcnt(0)
	s_setprio 1
	s_barrier
	v_mfma_f32_16x16x32_bf16 v[126:129], v[154:157], v[186:189], v[126:129]
	v_mfma_f32_16x16x32_bf16 v[122:125], v[162:165], v[186:189], v[122:125]
	v_mfma_f32_16x16x32_bf16 v[110:113], v[154:157], v[194:197], v[110:113]
	v_mfma_f32_16x16x32_bf16 v[106:109], v[162:165], v[194:197], v[106:109]
	v_mfma_f32_16x16x32_bf16 v[92:95], v[154:157], v[210:213], v[92:95]
	v_mfma_f32_16x16x32_bf16 v[88:91], v[162:165], v[210:213], v[88:91]
	v_mfma_f32_16x16x32_bf16 v[76:79], v[154:157], v[218:221], v[76:79]
	v_mfma_f32_16x16x32_bf16 v[72:75], v[162:165], v[218:221], v[72:75]
	v_mfma_f32_16x16x32_bf16 v[126:129], v[158:161], v[190:193], v[126:129]
	v_mfma_f32_16x16x32_bf16 v[122:125], v[166:169], v[190:193], v[122:125]
	v_mfma_f32_16x16x32_bf16 v[110:113], v[158:161], v[202:205], v[110:113]
	v_mfma_f32_16x16x32_bf16 v[106:109], v[166:169], v[202:205], v[106:109]
	v_mfma_f32_16x16x32_bf16 v[92:95], v[158:161], v[214:217], v[92:95]
	v_mfma_f32_16x16x32_bf16 v[88:91], v[166:169], v[214:217], v[88:91]
	v_mfma_f32_16x16x32_bf16 v[76:79], v[158:161], v[222:225], v[76:79]
	v_mfma_f32_16x16x32_bf16 v[72:75], v[166:169], v[222:225], v[72:75]
	v_mfma_f32_16x16x32_bf16 v[118:121], v[170:173], v[186:189], v[118:121]
	v_mfma_f32_16x16x32_bf16 v[114:117], v[178:181], v[186:189], v[114:117]
	v_mfma_f32_16x16x32_bf16 v[102:105], v[170:173], v[194:197], v[102:105]
	v_mfma_f32_16x16x32_bf16 v[98:101], v[178:181], v[194:197], v[98:101]
	v_mfma_f32_16x16x32_bf16 v[84:87], v[170:173], v[210:213], v[84:87]
	v_mfma_f32_16x16x32_bf16 v[80:83], v[178:181], v[210:213], v[80:83]
	v_mfma_f32_16x16x32_bf16 v[68:71], v[170:173], v[218:221], v[68:71]
	v_mfma_f32_16x16x32_bf16 v[64:67], v[178:181], v[218:221], v[64:67]
	v_mfma_f32_16x16x32_bf16 v[118:121], v[174:177], v[190:193], v[118:121]
	v_mfma_f32_16x16x32_bf16 v[114:117], v[182:185], v[190:193], v[114:117]
	v_mfma_f32_16x16x32_bf16 v[102:105], v[174:177], v[202:205], v[102:105]
	v_mfma_f32_16x16x32_bf16 v[98:101], v[182:185], v[202:205], v[98:101]
	v_mfma_f32_16x16x32_bf16 v[84:87], v[174:177], v[214:217], v[84:87]
	v_mfma_f32_16x16x32_bf16 v[80:83], v[182:185], v[214:217], v[80:83]
	v_mfma_f32_16x16x32_bf16 v[68:71], v[174:177], v[222:225], v[68:71]
	v_mfma_f32_16x16x32_bf16 v[64:67], v[182:185], v[222:225], v[64:67]
	s_barrier
	s_setprio 0
	s_add_i32 s33, s33, s75
	v_lshl_add_u64 v[144:145], v[144:145], 0, s[64:65]
	s_mov_b32 m0, s33
	ds_read_b128 v[186:189], v152 offset:49152
	ds_read_b128 v[190:193], v152 offset:50176
	ds_read_b128 v[194:197], v152 offset:51200
	ds_read_b128 v[202:205], v152 offset:52224
	ds_read_b128 v[210:213], v152 offset:53248
	ds_read_b128 v[214:217], v152 offset:54272
	ds_read_b128 v[218:221], v152 offset:55296
	ds_read_b128 v[222:225], v152 offset:56320
	global_load_lds_dwordx4 v[144:145], off
	s_add_i32 m0, s33, 0x2000
	s_add_u32 s38, s68, 0x80080
	v_lshl_add_u64 v[144:145], v[198:199], 0, s[64:65]
	s_addc_u32 s39, s69, 0
	s_add_i32 s33, s54, s75
	global_load_lds_dwordx4 v[144:145], off
	v_lshl_add_u64 v[144:145], s[38:39], 0, v[96:97]
	s_mov_b32 m0, s33
	s_nop 0
	global_load_lds_dwordx4 v[144:145], off
	v_lshl_add_u64 v[144:145], s[38:39], 0, v[134:135]
	s_add_i32 m0, s33, 0x2000
	s_nop 0
	global_load_lds_dwordx4 v[144:145], off
	v_lshl_add_u64 v[144:145], v[226:227], 0, s[64:65]
	s_mov_b32 m0, s58
	s_nop 0
	global_load_lds_dwordx4 v[144:145], off
	v_lshl_add_u64 v[144:145], v[228:229], 0, s[64:65]
	s_mov_b32 m0, s59
	s_nop 0
	global_load_lds_dwordx4 v[144:145], off
	s_waitcnt vmcnt(8)
	s_waitcnt lgkmcnt(0)
	s_setprio 1
	s_barrier
	v_mfma_f32_16x16x32_bf16 v[60:63], v[154:157], v[186:189], v[60:63]
	v_mfma_f32_16x16x32_bf16 v[56:59], v[162:165], v[186:189], v[56:59]
	v_mfma_f32_16x16x32_bf16 v[44:47], v[154:157], v[194:197], v[44:47]
	v_mfma_f32_16x16x32_bf16 v[40:43], v[162:165], v[194:197], v[40:43]
	v_mfma_f32_16x16x32_bf16 v[28:31], v[154:157], v[210:213], v[28:31]
	v_mfma_f32_16x16x32_bf16 v[24:27], v[162:165], v[210:213], v[24:27]
	v_mfma_f32_16x16x32_bf16 v[12:15], v[154:157], v[218:221], v[12:15]
	v_mfma_f32_16x16x32_bf16 v[8:11], v[162:165], v[218:221], v[8:11]
	v_mfma_f32_16x16x32_bf16 v[60:63], v[158:161], v[190:193], v[60:63]
	v_mfma_f32_16x16x32_bf16 v[56:59], v[166:169], v[190:193], v[56:59]
	v_mfma_f32_16x16x32_bf16 v[44:47], v[158:161], v[202:205], v[44:47]
	v_mfma_f32_16x16x32_bf16 v[40:43], v[166:169], v[202:205], v[40:43]
	v_mfma_f32_16x16x32_bf16 v[28:31], v[158:161], v[214:217], v[28:31]
	v_mfma_f32_16x16x32_bf16 v[24:27], v[166:169], v[214:217], v[24:27]
	v_mfma_f32_16x16x32_bf16 v[12:15], v[158:161], v[222:225], v[12:15]
	v_mfma_f32_16x16x32_bf16 v[8:11], v[166:169], v[222:225], v[8:11]
	v_mfma_f32_16x16x32_bf16 v[52:55], v[170:173], v[186:189], v[52:55]
	v_mfma_f32_16x16x32_bf16 v[48:51], v[178:181], v[186:189], v[48:51]
	v_mfma_f32_16x16x32_bf16 v[36:39], v[170:173], v[194:197], v[36:39]
	v_mfma_f32_16x16x32_bf16 v[32:35], v[178:181], v[194:197], v[32:35]
	v_mfma_f32_16x16x32_bf16 v[20:23], v[170:173], v[210:213], v[20:23]
	v_mfma_f32_16x16x32_bf16 v[16:19], v[178:181], v[210:213], v[16:19]
	v_mfma_f32_16x16x32_bf16 v[4:7], v[170:173], v[218:221], v[4:7]
	v_mfma_f32_16x16x32_bf16 v[0:3], v[178:181], v[218:221], v[0:3]
	v_mfma_f32_16x16x32_bf16 v[52:55], v[174:177], v[190:193], v[52:55]
	v_mfma_f32_16x16x32_bf16 v[48:51], v[182:185], v[190:193], v[48:51]
	v_mfma_f32_16x16x32_bf16 v[36:39], v[174:177], v[202:205], v[36:39]
	v_mfma_f32_16x16x32_bf16 v[32:35], v[182:185], v[202:205], v[32:35]
	v_mfma_f32_16x16x32_bf16 v[20:23], v[174:177], v[214:217], v[20:23]
	v_mfma_f32_16x16x32_bf16 v[16:19], v[182:185], v[214:217], v[16:19]
	v_mfma_f32_16x16x32_bf16 v[4:7], v[174:177], v[222:225], v[4:7]
	v_mfma_f32_16x16x32_bf16 v[0:3], v[182:185], v[222:225], v[0:3]
	s_barrier
	s_setprio 0
	s_add_i32 s28, s28, 2
	s_add_u32 s52, s52, 0x100
	s_addc_u32 s53, s53, 0
	s_add_u32 s20, s20, 0x100
	s_addc_u32 s25, s25, 0
	s_cmp_gt_u32 s28, 29
	s_cbranch_scc0 .LBB0_1284
	v_mov_b32_e32 v243, 1
	v_readlane_b32 s6, v251, 54
	v_readlane_b32 s7, v251, 55
	s_and_b64 vcc, exec, s[6:7]
	s_cbranch_vccz .LBB0_1287
	s_barrier
